# hgrn_sample rewritten by hand: all 32 state loads (dwordx4) issued up front, gate preamble batched into one round trip, ops read from LDS once per 4 key rows
# speedup vs baseline: 1.0250x; 1.0081x over previous
; #define LAS __attribute__((address_space(3)))
; #define GAS __attribute__((address_space(1)))
; __device__ __forceinline__ float sigm(float x) { return 1.0f / (1.0f + __expf(-x)); }
; #define LDS_WAIT() asm volatile("s_waitcnt lgkmcnt(0)" ::: "memory")
; __device__ __forceinline__ void hgrn_sample_wave(LAS float* buf, const GAS float* Z, const GAS float* logits, int layer, int b, int h, int vh, const GAS float* Sin, GAS float* Sout, GAS bf16* OPB, int lane) {
;     const int mbase = MP + b * 4;
; #pragma unroll
;     for (int t = 0; t < 4; ++t)
; #pragma unroll
;         for (int dd = 0; dd < 2; ++dd) { const int d = lane + 64 * dd, cfull = h * 128 + d; const float lb = hgrn_lb(logits, layer, cfull);
;             const float q = Z[(size_t)(mbase + t) * NCP + C_H + cfull], f = Z[(size_t)(mbase + t) * NCP + C_H + 512 + cfull], fg = lb + (1.0f - lb) * sigm(f);
;             *(LAS f32x4*)(buf + (t * 128 + d) * 4) = (f32x4){fg, 1.0f - fg, q * sigm(q), 0.f}; }
;     float vt[4], o[4];
; #pragma unroll
;     for (int t = 0; t < 4; ++t) { vt[t] = Z[(size_t)(mbase + t) * NCP + C_H + 1024 + h * 128 + vh * 64 + lane]; o[t] = 0.f; }
;     LDS_WAIT();
;     float Sn[8];
; #pragma unroll
;     for (int dd = 0; dd < 8; ++dd) Sn[dd] = __builtin_nontemporal_load(&Sin[dd * 128 + vh * 64 + lane]);
.LBB0_630:
	s_cmpk_gt_i32 s25, 0x3ff
	s_mov_b64 s[0:1], -1
	s_cbranch_scc0 .LBB0_650
	s_add_i32 s0, s25, 0xfffffc00
	s_lshr_b32 s14, s0, 1
	s_and_b32 s44, s14, 0x7ffffffc
	s_or_b32 s47, s44, 0x2000
	s_bfe_u32 s50, s25, 0x20001
	s_lshl_b32 s46, s50, 7
	s_lshl_b32 s14, s25, 6
	s_and_b32 s14, s14, 64
	s_load_dwordx2 s[18:19], s[28:29], 0x20
	s_load_dwordx2 s[16:17], s[28:29], 0x130
	s_mul_i32 s82, s47, 0x1500
	s_lshl_b64 s[0:1], s[82:83], 2
	s_add_u32 s2, s6, s0
	s_addc_u32 s3, s7, s1
	s_add_u32 s2, s2, 0x2a80
	s_addc_u32 s3, s3, 0
	v_add_lshl_u32 v16, s46, v191, 2
	s_add_i32 s4, s46, s14
	s_lshl_b32 s4, s4, 2
	s_addk_i32 s4, 0x1000
	v_and_b32_e32 v19, 15, v191
	v_lshrrev_b32_e32 v18, 4, v191
	v_lshl_add_u32 v176, v18, 4, s30
	v_lshlrev_b32_e32 v177, 9, v18
	v_lshl_add_u32 v177, v19, 4, v177
	v_lshl_add_u32 v18, v19, 4, s4
	v_mov_b32_e32 v168, 0
	v_mov_b32_e32 v169, 0
	s_andn2_b64 vcc, exec, s[68:69]
	s_cbranch_vccnz .Lhs_nolb
	global_load_dword v164, v16, s[26:27]
	global_load_dword v165, v16, s[26:27] offset:2048
	global_load_dword v166, v16, s[26:27] offset:256
	global_load_dword v167, v16, s[26:27] offset:2304
.Lhs_nolb:
	global_load_dword v0, v16, s[2:3]
	global_load_dword v1, v16, s[2:3] offset:256
	global_load_dword v2, v16, s[2:3] offset:2048
	global_load_dword v3, v16, s[2:3] offset:2304
	global_load_dwordx4 v[148:151], v18, s[2:3]
	s_add_u32 s2, s2, 0x5400
	s_addc_u32 s3, s3, 0
	global_load_dword v4, v16, s[2:3]
	global_load_dword v5, v16, s[2:3] offset:256
	global_load_dword v6, v16, s[2:3] offset:2048
	global_load_dword v7, v16, s[2:3] offset:2304
	global_load_dwordx4 v[152:155], v18, s[2:3]
	s_add_u32 s2, s2, 0x5400
	s_addc_u32 s3, s3, 0
	global_load_dword v8, v16, s[2:3]
	global_load_dword v9, v16, s[2:3] offset:256
	global_load_dword v10, v16, s[2:3] offset:2048
	global_load_dword v11, v16, s[2:3] offset:2304
	global_load_dwordx4 v[156:159], v18, s[2:3]
	s_add_u32 s2, s2, 0x5400
	s_addc_u32 s3, s3, 0
	global_load_dword v12, v16, s[2:3]
	global_load_dword v13, v16, s[2:3] offset:256
	global_load_dword v14, v16, s[2:3] offset:2048
	global_load_dword v15, v16, s[2:3] offset:2304
	global_load_dwordx4 v[160:163], v18, s[2:3]
	s_add_i32 s0, s44, s31
	s_or_b32 s0, s0, s50
	s_mov_b32 s1, 0
	s_lshl_b64 s[0:1], s[0:1], 16
	s_lshl_b32 s4, s14, 2
	s_add_u32 s0, s0, s4
	s_addc_u32 s1, s1, 0
	s_waitcnt lgkmcnt(0)
	s_add_u32 s18, s18, s0
	s_addc_u32 s19, s19, s1
	s_add_u32 s16, s16, s0
	s_addc_u32 s17, s17, s1
	s_add_u32 s16, s16, 0x68f1400
	s_addc_u32 s17, s17, 0
	global_load_dwordx4 v[20:23], v177, s[18:19] nt
	s_add_u32 s18, s18, 0x800
	s_addc_u32 s19, s19, 0
	global_load_dwordx4 v[24:27], v177, s[18:19] nt
	s_add_u32 s18, s18, 0x800
	s_addc_u32 s19, s19, 0
	global_load_dwordx4 v[28:31], v177, s[18:19] nt
	s_add_u32 s18, s18, 0x800
	s_addc_u32 s19, s19, 0
	global_load_dwordx4 v[32:35], v177, s[18:19] nt
	s_add_u32 s18, s18, 0x800
	s_addc_u32 s19, s19, 0
	global_load_dwordx4 v[36:39], v177, s[18:19] nt
	s_add_u32 s18, s18, 0x800
	s_addc_u32 s19, s19, 0
	global_load_dwordx4 v[40:43], v177, s[18:19] nt
	s_add_u32 s18, s18, 0x800
	s_addc_u32 s19, s19, 0
	global_load_dwordx4 v[44:47], v177, s[18:19] nt
	s_add_u32 s18, s18, 0x800
	s_addc_u32 s19, s19, 0
	global_load_dwordx4 v[48:51], v177, s[18:19] nt
	s_add_u32 s18, s18, 0x800
	s_addc_u32 s19, s19, 0
	global_load_dwordx4 v[52:55], v177, s[18:19] nt
	s_add_u32 s18, s18, 0x800
	s_addc_u32 s19, s19, 0
	global_load_dwordx4 v[56:59], v177, s[18:19] nt
	s_add_u32 s18, s18, 0x800
	s_addc_u32 s19, s19, 0
	global_load_dwordx4 v[60:63], v177, s[18:19] nt
	s_add_u32 s18, s18, 0x800
	s_addc_u32 s19, s19, 0
	global_load_dwordx4 v[64:67], v177, s[18:19] nt
	s_add_u32 s18, s18, 0x800
	s_addc_u32 s19, s19, 0
	global_load_dwordx4 v[68:71], v177, s[18:19] nt
	s_add_u32 s18, s18, 0x800
	s_addc_u32 s19, s19, 0
	global_load_dwordx4 v[72:75], v177, s[18:19] nt
	s_add_u32 s18, s18, 0x800
	s_addc_u32 s19, s19, 0
	global_load_dwordx4 v[76:79], v177, s[18:19] nt
	s_add_u32 s18, s18, 0x800
	s_addc_u32 s19, s19, 0
	global_load_dwordx4 v[80:83], v177, s[18:19] nt
	s_add_u32 s18, s18, 0x800
	s_addc_u32 s19, s19, 0
	global_load_dwordx4 v[84:87], v177, s[18:19] nt
	s_add_u32 s18, s18, 0x800
	s_addc_u32 s19, s19, 0
	global_load_dwordx4 v[88:91], v177, s[18:19] nt
	s_add_u32 s18, s18, 0x800
	s_addc_u32 s19, s19, 0
	global_load_dwordx4 v[92:95], v177, s[18:19] nt
	s_add_u32 s18, s18, 0x800
	s_addc_u32 s19, s19, 0
	global_load_dwordx4 v[96:99], v177, s[18:19] nt
	s_add_u32 s18, s18, 0x800
	s_addc_u32 s19, s19, 0
	global_load_dwordx4 v[100:103], v177, s[18:19] nt
	s_add_u32 s18, s18, 0x800
	s_addc_u32 s19, s19, 0
	global_load_dwordx4 v[104:107], v177, s[18:19] nt
	s_add_u32 s18, s18, 0x800
	s_addc_u32 s19, s19, 0
	global_load_dwordx4 v[108:111], v177, s[18:19] nt
	s_add_u32 s18, s18, 0x800
	s_addc_u32 s19, s19, 0
	global_load_dwordx4 v[112:115], v177, s[18:19] nt
	s_add_u32 s18, s18, 0x800
	s_addc_u32 s19, s19, 0
	global_load_dwordx4 v[116:119], v177, s[18:19] nt
	s_add_u32 s18, s18, 0x800
	s_addc_u32 s19, s19, 0
	global_load_dwordx4 v[120:123], v177, s[18:19] nt
	s_add_u32 s18, s18, 0x800
	s_addc_u32 s19, s19, 0
	global_load_dwordx4 v[124:127], v177, s[18:19] nt
	s_add_u32 s18, s18, 0x800
	s_addc_u32 s19, s19, 0
	global_load_dwordx4 v[128:131], v177, s[18:19] nt
	s_add_u32 s18, s18, 0x800
	s_addc_u32 s19, s19, 0
	global_load_dwordx4 v[132:135], v177, s[18:19] nt
	s_add_u32 s18, s18, 0x800
	s_addc_u32 s19, s19, 0
	global_load_dwordx4 v[136:139], v177, s[18:19] nt
	s_add_u32 s18, s18, 0x800
	s_addc_u32 s19, s19, 0
	global_load_dwordx4 v[140:143], v177, s[18:19] nt
	s_add_u32 s18, s18, 0x800
	s_addc_u32 s19, s19, 0
	global_load_dwordx4 v[144:147], v177, s[18:19] nt
	s_andn2_b64 vcc, exec, s[68:69]
	s_cbranch_vccnz .Lhs_lbdone
	s_waitcnt vmcnt(52)
	v_sub_f32_e32 v175, v164, v165
	v_mul_f32_e32 v175, 0x3fb8aa3b, v175
	v_exp_f32_e32 v175, v175
	s_nop 0
	v_add_f32_e32 v175, 1.0, v175
	v_div_scale_f32 v170, s[4:5], v175, v175, 1.0
	v_rcp_f32_e32 v171, v170
	v_div_scale_f32 v172, vcc, 1.0, v175, 1.0
	v_fma_f32 v173, -v170, v171, 1.0
	v_fmac_f32_e32 v171, v173, v171
	v_mul_f32_e32 v173, v172, v171
	v_fma_f32 v174, -v170, v173, v172
	v_fmac_f32_e32 v173, v174, v171
	v_fma_f32 v170, -v170, v173, v172
	v_div_fmas_f32 v170, v170, v171, v173
	v_div_fixup_f32 v168, v170, v175, 1.0
	v_sub_f32_e32 v175, v166, v167
	v_mul_f32_e32 v175, 0x3fb8aa3b, v175
	v_exp_f32_e32 v175, v175
	s_nop 0
	v_add_f32_e32 v175, 1.0, v175
	v_div_scale_f32 v170, s[4:5], v175, v175, 1.0
	v_rcp_f32_e32 v171, v170
	v_div_scale_f32 v172, vcc, 1.0, v175, 1.0
	v_fma_f32 v173, -v170, v171, 1.0
	v_fmac_f32_e32 v171, v173, v171
	v_mul_f32_e32 v173, v172, v171
	v_fma_f32 v174, -v170, v173, v172
	v_fmac_f32_e32 v173, v174, v171
	v_fma_f32 v170, -v170, v173, v172
	v_div_fmas_f32 v170, v170, v171, v173
	v_div_fixup_f32 v169, v170, v175, 1.0
; #define LAS __attribute__((address_space(3)))
; __device__ __forceinline__ float sigm(float x) { return 1.0f / (1.0f + __expf(-x)); }
; __device__ __forceinline__ void hgrn_sample_wave(LAS float* buf, const GAS float* Z, const GAS float* logits, int layer, int b, int h, int vh, const GAS float* Sin, GAS float* Sout, GAS bf16* OPB, int lane) {
;     ...
; #pragma unroll
;     for (int t = 0; t < 4; ++t)
; #pragma unroll
;         for (int dd = 0; dd < 2; ++dd) { const int d = lane + 64 * dd, cfull = h * 128 + d; const float lb = hgrn_lb(logits, layer, cfull);
;             const float q = Z[(size_t)(mbase + t) * NCP + C_H + cfull], f = Z[(size_t)(mbase + t) * NCP + C_H + 512 + cfull], fg = lb + (1.0f - lb) * sigm(f);
;             *(LAS f32x4*)(buf + (t * 128 + d) * 4) = (f32x4){fg, 1.0f - fg, q * sigm(q), 0.f}; }
.Lhs_lbdone:
	v_sub_f32_e32 v166, 1.0, v168
	v_sub_f32_e32 v167, 1.0, v169
	v_lshl_add_u32 v19, v191, 4, s30
	s_waitcnt vmcnt(32)
	v_mul_f32_e32 v175, 0xbfb8aa3b, v2
	v_exp_f32_e32 v175, v175
	s_nop 0
	v_add_f32_e32 v175, 1.0, v175
	v_div_scale_f32 v170, s[4:5], v175, v175, 1.0
	v_rcp_f32_e32 v171, v170
	v_div_scale_f32 v172, vcc, 1.0, v175, 1.0
	v_fma_f32 v173, -v170, v171, 1.0
	v_fmac_f32_e32 v171, v173, v171
	v_mul_f32_e32 v173, v172, v171
	v_fma_f32 v174, -v170, v173, v172
	v_fmac_f32_e32 v173, v174, v171
	v_fma_f32 v170, -v170, v173, v172
	v_div_fmas_f32 v170, v170, v171, v173
	v_div_fixup_f32 v164, v170, v175, 1.0
	v_mov_b32_e32 v2, v168
	v_fmac_f32_e32 v2, v166, v164
	v_mul_f32_e32 v175, 0xbfb8aa3b, v0
	v_exp_f32_e32 v175, v175
	s_nop 0
	v_add_f32_e32 v175, 1.0, v175
	v_div_scale_f32 v170, s[4:5], v175, v175, 1.0
	v_rcp_f32_e32 v171, v170
	v_div_scale_f32 v172, vcc, 1.0, v175, 1.0
	v_fma_f32 v173, -v170, v171, 1.0
	v_fmac_f32_e32 v171, v173, v171
	v_mul_f32_e32 v173, v172, v171
	v_fma_f32 v174, -v170, v173, v172
	v_fmac_f32_e32 v173, v174, v171
	v_fma_f32 v170, -v170, v173, v172
	v_div_fmas_f32 v170, v170, v171, v173
	v_div_fixup_f32 v164, v170, v175, 1.0
	v_mul_f32_e32 v174, v0, v164
	v_mov_b32_e32 v172, v2
	v_sub_f32_e32 v173, 1.0, v2
	v_mov_b32_e32 v175, 0
	ds_write_b128 v19, v[172:175] offset:0
	v_mul_f32_e32 v175, 0xbfb8aa3b, v3
	v_exp_f32_e32 v175, v175
	s_nop 0
	v_add_f32_e32 v175, 1.0, v175
	v_div_scale_f32 v170, s[4:5], v175, v175, 1.0
	v_rcp_f32_e32 v171, v170
	v_div_scale_f32 v172, vcc, 1.0, v175, 1.0
	v_fma_f32 v173, -v170, v171, 1.0
	v_fmac_f32_e32 v171, v173, v171
	v_mul_f32_e32 v173, v172, v171
	v_fma_f32 v174, -v170, v173, v172
	v_fmac_f32_e32 v173, v174, v171
	v_fma_f32 v170, -v170, v173, v172
	v_div_fmas_f32 v170, v170, v171, v173
	v_div_fixup_f32 v164, v170, v175, 1.0
	v_mov_b32_e32 v3, v169
	v_fmac_f32_e32 v3, v167, v164
	v_mul_f32_e32 v175, 0xbfb8aa3b, v1
	v_exp_f32_e32 v175, v175
	s_nop 0
	v_add_f32_e32 v175, 1.0, v175
	v_div_scale_f32 v170, s[4:5], v175, v175, 1.0
	v_rcp_f32_e32 v171, v170
	v_div_scale_f32 v172, vcc, 1.0, v175, 1.0
	v_fma_f32 v173, -v170, v171, 1.0
	v_fmac_f32_e32 v171, v173, v171
	v_mul_f32_e32 v173, v172, v171
	v_fma_f32 v174, -v170, v173, v172
	v_fmac_f32_e32 v173, v174, v171
	v_fma_f32 v170, -v170, v173, v172
	v_div_fmas_f32 v170, v170, v171, v173
	v_div_fixup_f32 v164, v170, v175, 1.0
	v_mul_f32_e32 v174, v1, v164
	v_mov_b32_e32 v172, v3
	v_sub_f32_e32 v173, 1.0, v3
	v_mov_b32_e32 v175, 0
	ds_write_b128 v19, v[172:175] offset:1024
	v_mul_f32_e32 v175, 0xbfb8aa3b, v6
	v_exp_f32_e32 v175, v175
	s_nop 0
	v_add_f32_e32 v175, 1.0, v175
	v_div_scale_f32 v170, s[4:5], v175, v175, 1.0
	v_rcp_f32_e32 v171, v170
	v_div_scale_f32 v172, vcc, 1.0, v175, 1.0
	v_fma_f32 v173, -v170, v171, 1.0
	v_fmac_f32_e32 v171, v173, v171
	v_mul_f32_e32 v173, v172, v171
	v_fma_f32 v174, -v170, v173, v172
	v_fmac_f32_e32 v173, v174, v171
	v_fma_f32 v170, -v170, v173, v172
	v_div_fmas_f32 v170, v170, v171, v173
	v_div_fixup_f32 v164, v170, v175, 1.0
	v_mov_b32_e32 v6, v168
	v_fmac_f32_e32 v6, v166, v164
	v_mul_f32_e32 v175, 0xbfb8aa3b, v4
	v_exp_f32_e32 v175, v175
	s_nop 0
	v_add_f32_e32 v175, 1.0, v175
	v_div_scale_f32 v170, s[4:5], v175, v175, 1.0
	v_rcp_f32_e32 v171, v170
	v_div_scale_f32 v172, vcc, 1.0, v175, 1.0
	v_fma_f32 v173, -v170, v171, 1.0
	v_fmac_f32_e32 v171, v173, v171
	v_mul_f32_e32 v173, v172, v171
	v_fma_f32 v174, -v170, v173, v172
	v_fmac_f32_e32 v173, v174, v171
	v_fma_f32 v170, -v170, v173, v172
	v_div_fmas_f32 v170, v170, v171, v173
	v_div_fixup_f32 v164, v170, v175, 1.0
	v_mul_f32_e32 v174, v4, v164
	v_mov_b32_e32 v172, v6
	v_sub_f32_e32 v173, 1.0, v6
	v_mov_b32_e32 v175, 0
	ds_write_b128 v19, v[172:175] offset:2048
	v_mul_f32_e32 v175, 0xbfb8aa3b, v7
	v_exp_f32_e32 v175, v175
	s_nop 0
	v_add_f32_e32 v175, 1.0, v175
	v_div_scale_f32 v170, s[4:5], v175, v175, 1.0
	v_rcp_f32_e32 v171, v170
	v_div_scale_f32 v172, vcc, 1.0, v175, 1.0
	v_fma_f32 v173, -v170, v171, 1.0
	v_fmac_f32_e32 v171, v173, v171
	v_mul_f32_e32 v173, v172, v171
	v_fma_f32 v174, -v170, v173, v172
	v_fmac_f32_e32 v173, v174, v171
	v_fma_f32 v170, -v170, v173, v172
	v_div_fmas_f32 v170, v170, v171, v173
	v_div_fixup_f32 v164, v170, v175, 1.0
	v_mov_b32_e32 v7, v169
	v_fmac_f32_e32 v7, v167, v164
	v_mul_f32_e32 v175, 0xbfb8aa3b, v5
	v_exp_f32_e32 v175, v175
	s_nop 0
	v_add_f32_e32 v175, 1.0, v175
	v_div_scale_f32 v170, s[4:5], v175, v175, 1.0
	v_rcp_f32_e32 v171, v170
	v_div_scale_f32 v172, vcc, 1.0, v175, 1.0
	v_fma_f32 v173, -v170, v171, 1.0
	v_fmac_f32_e32 v171, v173, v171
	v_mul_f32_e32 v173, v172, v171
	v_fma_f32 v174, -v170, v173, v172
	v_fmac_f32_e32 v173, v174, v171
	v_fma_f32 v170, -v170, v173, v172
	v_div_fmas_f32 v170, v170, v171, v173
	v_div_fixup_f32 v164, v170, v175, 1.0
	v_mul_f32_e32 v174, v5, v164
	v_mov_b32_e32 v172, v7
	v_sub_f32_e32 v173, 1.0, v7
	v_mov_b32_e32 v175, 0
	ds_write_b128 v19, v[172:175] offset:3072
	v_mul_f32_e32 v175, 0xbfb8aa3b, v10
	v_exp_f32_e32 v175, v175
	s_nop 0
	v_add_f32_e32 v175, 1.0, v175
	v_div_scale_f32 v170, s[4:5], v175, v175, 1.0
	v_rcp_f32_e32 v171, v170
	v_div_scale_f32 v172, vcc, 1.0, v175, 1.0
	v_fma_f32 v173, -v170, v171, 1.0
	v_fmac_f32_e32 v171, v173, v171
	v_mul_f32_e32 v173, v172, v171
	v_fma_f32 v174, -v170, v173, v172
	v_fmac_f32_e32 v173, v174, v171
	v_fma_f32 v170, -v170, v173, v172
	v_div_fmas_f32 v170, v170, v171, v173
	v_div_fixup_f32 v164, v170, v175, 1.0
	v_mov_b32_e32 v10, v168
	v_fmac_f32_e32 v10, v166, v164
	v_mul_f32_e32 v175, 0xbfb8aa3b, v8
	v_exp_f32_e32 v175, v175
	s_nop 0
	v_add_f32_e32 v175, 1.0, v175
	v_div_scale_f32 v170, s[4:5], v175, v175, 1.0
; #define LAS __attribute__((address_space(3)))
; __device__ __forceinline__ float sigm(float x) { return 1.0f / (1.0f + __expf(-x)); }
; #define LDS_WAIT() asm volatile("s_waitcnt lgkmcnt(0)" ::: "memory")
; __device__ __forceinline__ void hgrn_sample_wave(LAS float* buf, const GAS float* Z, const GAS float* logits, int layer, int b, int h, int vh, const GAS float* Sin, GAS float* Sout, GAS bf16* OPB, int lane) {
;     ...
;         for (int dd = 0; dd < 2; ++dd) { const int d = lane + 64 * dd, cfull = h * 128 + d; const float lb = hgrn_lb(logits, layer, cfull);
;             const float q = Z[(size_t)(mbase + t) * NCP + C_H + cfull], f = Z[(size_t)(mbase + t) * NCP + C_H + 512 + cfull], fg = lb + (1.0f - lb) * sigm(f);
;             *(LAS f32x4*)(buf + (t * 128 + d) * 4) = (f32x4){fg, 1.0f - fg, q * sigm(q), 0.f}; }
;     float vt[4], o[4];
; #pragma unroll
;     for (int t = 0; t < 4; ++t) { vt[t] = Z[(size_t)(mbase + t) * NCP + C_H + 1024 + h * 128 + vh * 64 + lane]; o[t] = 0.f; }
;     LDS_WAIT();
;     float Sn[8];
; #pragma unroll
;     for (int dd = 0; dd < 8; ++dd) Sn[dd] = __builtin_nontemporal_load(&Sin[dd * 128 + vh * 64 + lane]);
;     for (int dc = 0; dc < 16; ++dc) { float S[8];
; #pragma unroll
;         for (int dd = 0; dd < 8; ++dd) S[dd] = Sn[dd];
;         if (dc + 1 < 16) {
; #pragma unroll
;             for (int dd = 0; dd < 8; ++dd) Sn[dd] = __builtin_nontemporal_load(&Sin[((dc + 1) * 8 + dd) * 128 + vh * 64 + lane]); }
; #pragma unroll
;         for (int t = 0; t < 4; ++t)
; #pragma unroll
;             for (int dd = 0; dd < 8; ++dd) { const f32x4 op = *(const LAS f32x4*)(buf + (t * 128 + dc * 8 + dd) * 4); S[dd] = op.x * S[dd] + op.y * vt[t]; o[t] += op.z * S[dd]; }
	v_rcp_f32_e32 v171, v170
	v_div_scale_f32 v172, vcc, 1.0, v175, 1.0
	v_fma_f32 v173, -v170, v171, 1.0
	v_fmac_f32_e32 v171, v173, v171
	v_mul_f32_e32 v173, v172, v171
	v_fma_f32 v174, -v170, v173, v172
	v_fmac_f32_e32 v173, v174, v171
	v_fma_f32 v170, -v170, v173, v172
	v_div_fmas_f32 v170, v170, v171, v173
	v_div_fixup_f32 v164, v170, v175, 1.0
	v_mul_f32_e32 v174, v8, v164
	v_mov_b32_e32 v172, v10
	v_sub_f32_e32 v173, 1.0, v10
	v_mov_b32_e32 v175, 0
	ds_write_b128 v19, v[172:175] offset:4096
	v_mul_f32_e32 v175, 0xbfb8aa3b, v11
	v_exp_f32_e32 v175, v175
	s_nop 0
	v_add_f32_e32 v175, 1.0, v175
	v_div_scale_f32 v170, s[4:5], v175, v175, 1.0
	v_rcp_f32_e32 v171, v170
	v_div_scale_f32 v172, vcc, 1.0, v175, 1.0
	v_fma_f32 v173, -v170, v171, 1.0
	v_fmac_f32_e32 v171, v173, v171
	v_mul_f32_e32 v173, v172, v171
	v_fma_f32 v174, -v170, v173, v172
	v_fmac_f32_e32 v173, v174, v171
	v_fma_f32 v170, -v170, v173, v172
	v_div_fmas_f32 v170, v170, v171, v173
	v_div_fixup_f32 v164, v170, v175, 1.0
	v_mov_b32_e32 v11, v169
	v_fmac_f32_e32 v11, v167, v164
	v_mul_f32_e32 v175, 0xbfb8aa3b, v9
	v_exp_f32_e32 v175, v175
	s_nop 0
	v_add_f32_e32 v175, 1.0, v175
	v_div_scale_f32 v170, s[4:5], v175, v175, 1.0
	v_rcp_f32_e32 v171, v170
	v_div_scale_f32 v172, vcc, 1.0, v175, 1.0
	v_fma_f32 v173, -v170, v171, 1.0
	v_fmac_f32_e32 v171, v173, v171
	v_mul_f32_e32 v173, v172, v171
	v_fma_f32 v174, -v170, v173, v172
	v_fmac_f32_e32 v173, v174, v171
	v_fma_f32 v170, -v170, v173, v172
	v_div_fmas_f32 v170, v170, v171, v173
	v_div_fixup_f32 v164, v170, v175, 1.0
	v_mul_f32_e32 v174, v9, v164
	v_mov_b32_e32 v172, v11
	v_sub_f32_e32 v173, 1.0, v11
	v_mov_b32_e32 v175, 0
	ds_write_b128 v19, v[172:175] offset:5120
	v_mul_f32_e32 v175, 0xbfb8aa3b, v14
	v_exp_f32_e32 v175, v175
	s_nop 0
	v_add_f32_e32 v175, 1.0, v175
	v_div_scale_f32 v170, s[4:5], v175, v175, 1.0
	v_rcp_f32_e32 v171, v170
	v_div_scale_f32 v172, vcc, 1.0, v175, 1.0
	v_fma_f32 v173, -v170, v171, 1.0
	v_fmac_f32_e32 v171, v173, v171
	v_mul_f32_e32 v173, v172, v171
	v_fma_f32 v174, -v170, v173, v172
	v_fmac_f32_e32 v173, v174, v171
	v_fma_f32 v170, -v170, v173, v172
	v_div_fmas_f32 v170, v170, v171, v173
	v_div_fixup_f32 v164, v170, v175, 1.0
	v_mov_b32_e32 v14, v168
	v_fmac_f32_e32 v14, v166, v164
	v_mul_f32_e32 v175, 0xbfb8aa3b, v12
	v_exp_f32_e32 v175, v175
	s_nop 0
	v_add_f32_e32 v175, 1.0, v175
	v_div_scale_f32 v170, s[4:5], v175, v175, 1.0
	v_rcp_f32_e32 v171, v170
	v_div_scale_f32 v172, vcc, 1.0, v175, 1.0
	v_fma_f32 v173, -v170, v171, 1.0
	v_fmac_f32_e32 v171, v173, v171
	v_mul_f32_e32 v173, v172, v171
	v_fma_f32 v174, -v170, v173, v172
	v_fmac_f32_e32 v173, v174, v171
	v_fma_f32 v170, -v170, v173, v172
	v_div_fmas_f32 v170, v170, v171, v173
	v_div_fixup_f32 v164, v170, v175, 1.0
	v_mul_f32_e32 v174, v12, v164
	v_mov_b32_e32 v172, v14
	v_sub_f32_e32 v173, 1.0, v14
	v_mov_b32_e32 v175, 0
	ds_write_b128 v19, v[172:175] offset:6144
	v_mul_f32_e32 v175, 0xbfb8aa3b, v15
	v_exp_f32_e32 v175, v175
	s_nop 0
	v_add_f32_e32 v175, 1.0, v175
	v_div_scale_f32 v170, s[4:5], v175, v175, 1.0
	v_rcp_f32_e32 v171, v170
	v_div_scale_f32 v172, vcc, 1.0, v175, 1.0
	v_fma_f32 v173, -v170, v171, 1.0
	v_fmac_f32_e32 v171, v173, v171
	v_mul_f32_e32 v173, v172, v171
	v_fma_f32 v174, -v170, v173, v172
	v_fmac_f32_e32 v173, v174, v171
	v_fma_f32 v170, -v170, v173, v172
	v_div_fmas_f32 v170, v170, v171, v173
	v_div_fixup_f32 v164, v170, v175, 1.0
	v_mov_b32_e32 v15, v169
	v_fmac_f32_e32 v15, v167, v164
	v_mul_f32_e32 v175, 0xbfb8aa3b, v13
	v_exp_f32_e32 v175, v175
	s_nop 0
	v_add_f32_e32 v175, 1.0, v175
	v_div_scale_f32 v170, s[4:5], v175, v175, 1.0
	v_rcp_f32_e32 v171, v170
	v_div_scale_f32 v172, vcc, 1.0, v175, 1.0
	v_fma_f32 v173, -v170, v171, 1.0
	v_fmac_f32_e32 v171, v173, v171
	v_mul_f32_e32 v173, v172, v171
	v_fma_f32 v174, -v170, v173, v172
	v_fmac_f32_e32 v173, v174, v171
	v_fma_f32 v170, -v170, v173, v172
	v_div_fmas_f32 v170, v170, v171, v173
	v_div_fixup_f32 v164, v170, v175, 1.0
	v_mul_f32_e32 v174, v13, v164
	v_mov_b32_e32 v172, v15
	v_sub_f32_e32 v173, 1.0, v15
	v_mov_b32_e32 v175, 0
	ds_write_b128 v19, v[172:175] offset:7168
	v_mov_b32_e32 v0, 0
	v_mov_b32_e32 v1, 0
	v_mov_b32_e32 v2, 0
	v_mov_b32_e32 v3, 0
	v_mov_b32_e32 v4, 0
	v_mov_b32_e32 v5, 0
	v_mov_b32_e32 v6, 0
	v_mov_b32_e32 v7, 0
	v_mov_b32_e32 v8, 0
	v_mov_b32_e32 v9, 0
	v_mov_b32_e32 v10, 0
	v_mov_b32_e32 v11, 0
	v_mov_b32_e32 v12, 0
	v_mov_b32_e32 v13, 0
	v_mov_b32_e32 v14, 0
	v_mov_b32_e32 v15, 0
	s_waitcnt lgkmcnt(0)
	ds_read_b128 v[164:167], v176 offset:0
	ds_read_b128 v[168:171], v176 offset:2048
	s_waitcnt vmcnt(31)
	s_waitcnt lgkmcnt(1)
	v_pk_mul_f32 v[172:173], v[164:165], v[148:149] op_sel:[1,0] op_sel_hi:[1,1]
	v_pk_mul_f32 v[174:175], v[164:165], v[150:151] op_sel:[1,0] op_sel_hi:[1,1]
	v_pk_fma_f32 v[20:21], v[164:165], v[20:21], v[172:173] op_sel_hi:[0,1,1]
	v_pk_fma_f32 v[22:23], v[164:165], v[22:23], v[174:175] op_sel_hi:[0,1,1]
	v_pk_fma_f32 v[0:1], v[166:167], v[20:21], v[0:1] op_sel_hi:[0,1,1]
	v_pk_fma_f32 v[2:3], v[166:167], v[22:23], v[2:3] op_sel_hi:[0,1,1]
	ds_read_b128 v[164:167], v176 offset:4096
	s_waitcnt lgkmcnt(1)
	v_pk_mul_f32 v[172:173], v[168:169], v[152:153] op_sel:[1,0] op_sel_hi:[1,1]
	v_pk_mul_f32 v[174:175], v[168:169], v[154:155] op_sel:[1,0] op_sel_hi:[1,1]
	v_pk_fma_f32 v[20:21], v[168:169], v[20:21], v[172:173] op_sel_hi:[0,1,1]
	v_pk_fma_f32 v[22:23], v[168:169], v[22:23], v[174:175] op_sel_hi:[0,1,1]
	v_pk_fma_f32 v[4:5], v[170:171], v[20:21], v[4:5] op_sel_hi:[0,1,1]
	v_pk_fma_f32 v[6:7], v[170:171], v[22:23], v[6:7] op_sel_hi:[0,1,1]
	ds_read_b128 v[168:171], v176 offset:6144
	s_waitcnt lgkmcnt(1)
; #define LAS __attribute__((address_space(3)))
; __device__ __forceinline__ void hgrn_sample_wave(LAS float* buf, const GAS float* Z, const GAS float* logits, int layer, int b, int h, int vh, const GAS float* Sin, GAS float* Sout, GAS bf16* OPB, int lane) {
;     ...
;     for (int dc = 0; dc < 16; ++dc) { float S[8];
; #pragma unroll
;         for (int dd = 0; dd < 8; ++dd) S[dd] = Sn[dd];
;         if (dc + 1 < 16) {
; #pragma unroll
;             for (int dd = 0; dd < 8; ++dd) Sn[dd] = __builtin_nontemporal_load(&Sin[((dc + 1) * 8 + dd) * 128 + vh * 64 + lane]); }
; #pragma unroll
;         for (int t = 0; t < 4; ++t)
; #pragma unroll
;             for (int dd = 0; dd < 8; ++dd) { const f32x4 op = *(const LAS f32x4*)(buf + (t * 128 + dc * 8 + dd) * 4); S[dd] = op.x * S[dd] + op.y * vt[t]; o[t] += op.z * S[dd]; }
; #pragma unroll
;         for (int dd = 0; dd < 8; ++dd) __builtin_nontemporal_store(S[dd], &Sout[(dc * 8 + dd) * 128 + vh * 64 + lane]); }
	v_pk_mul_f32 v[172:173], v[164:165], v[156:157] op_sel:[1,0] op_sel_hi:[1,1]
	v_pk_mul_f32 v[174:175], v[164:165], v[158:159] op_sel:[1,0] op_sel_hi:[1,1]
	v_pk_fma_f32 v[20:21], v[164:165], v[20:21], v[172:173] op_sel_hi:[0,1,1]
	v_pk_fma_f32 v[22:23], v[164:165], v[22:23], v[174:175] op_sel_hi:[0,1,1]
	v_pk_fma_f32 v[8:9], v[166:167], v[20:21], v[8:9] op_sel_hi:[0,1,1]
	v_pk_fma_f32 v[10:11], v[166:167], v[22:23], v[10:11] op_sel_hi:[0,1,1]
	ds_read_b128 v[164:167], v176 offset:64
	s_waitcnt lgkmcnt(1)
	v_pk_mul_f32 v[172:173], v[168:169], v[160:161] op_sel:[1,0] op_sel_hi:[1,1]
	v_pk_mul_f32 v[174:175], v[168:169], v[162:163] op_sel:[1,0] op_sel_hi:[1,1]
	v_pk_fma_f32 v[20:21], v[168:169], v[20:21], v[172:173] op_sel_hi:[0,1,1]
	v_pk_fma_f32 v[22:23], v[168:169], v[22:23], v[174:175] op_sel_hi:[0,1,1]
	v_pk_fma_f32 v[12:13], v[170:171], v[20:21], v[12:13] op_sel_hi:[0,1,1]
	v_pk_fma_f32 v[14:15], v[170:171], v[22:23], v[14:15] op_sel_hi:[0,1,1]
	ds_read_b128 v[168:171], v176 offset:2112
	global_store_dwordx4 v177, v[20:23], s[16:17] nt
	s_add_u32 s16, s16, 0x800
	s_addc_u32 s17, s17, 0
	s_waitcnt vmcnt(31)
	s_waitcnt lgkmcnt(1)
	v_pk_mul_f32 v[172:173], v[164:165], v[148:149] op_sel:[1,0] op_sel_hi:[1,1]
	v_pk_mul_f32 v[174:175], v[164:165], v[150:151] op_sel:[1,0] op_sel_hi:[1,1]
	v_pk_fma_f32 v[24:25], v[164:165], v[24:25], v[172:173] op_sel_hi:[0,1,1]
	v_pk_fma_f32 v[26:27], v[164:165], v[26:27], v[174:175] op_sel_hi:[0,1,1]
	v_pk_fma_f32 v[0:1], v[166:167], v[24:25], v[0:1] op_sel_hi:[0,1,1]
	v_pk_fma_f32 v[2:3], v[166:167], v[26:27], v[2:3] op_sel_hi:[0,1,1]
	ds_read_b128 v[164:167], v176 offset:4160
	s_waitcnt lgkmcnt(1)
	v_pk_mul_f32 v[172:173], v[168:169], v[152:153] op_sel:[1,0] op_sel_hi:[1,1]
	v_pk_mul_f32 v[174:175], v[168:169], v[154:155] op_sel:[1,0] op_sel_hi:[1,1]
	v_pk_fma_f32 v[24:25], v[168:169], v[24:25], v[172:173] op_sel_hi:[0,1,1]
	v_pk_fma_f32 v[26:27], v[168:169], v[26:27], v[174:175] op_sel_hi:[0,1,1]
	v_pk_fma_f32 v[4:5], v[170:171], v[24:25], v[4:5] op_sel_hi:[0,1,1]
	v_pk_fma_f32 v[6:7], v[170:171], v[26:27], v[6:7] op_sel_hi:[0,1,1]
	ds_read_b128 v[168:171], v176 offset:6208
	s_waitcnt lgkmcnt(1)
	v_pk_mul_f32 v[172:173], v[164:165], v[156:157] op_sel:[1,0] op_sel_hi:[1,1]
	v_pk_mul_f32 v[174:175], v[164:165], v[158:159] op_sel:[1,0] op_sel_hi:[1,1]
	v_pk_fma_f32 v[24:25], v[164:165], v[24:25], v[172:173] op_sel_hi:[0,1,1]
	v_pk_fma_f32 v[26:27], v[164:165], v[26:27], v[174:175] op_sel_hi:[0,1,1]
	v_pk_fma_f32 v[8:9], v[166:167], v[24:25], v[8:9] op_sel_hi:[0,1,1]
	v_pk_fma_f32 v[10:11], v[166:167], v[26:27], v[10:11] op_sel_hi:[0,1,1]
	ds_read_b128 v[164:167], v176 offset:128
	s_waitcnt lgkmcnt(1)
	v_pk_mul_f32 v[172:173], v[168:169], v[160:161] op_sel:[1,0] op_sel_hi:[1,1]
	v_pk_mul_f32 v[174:175], v[168:169], v[162:163] op_sel:[1,0] op_sel_hi:[1,1]
	v_pk_fma_f32 v[24:25], v[168:169], v[24:25], v[172:173] op_sel_hi:[0,1,1]
	v_pk_fma_f32 v[26:27], v[168:169], v[26:27], v[174:175] op_sel_hi:[0,1,1]
	v_pk_fma_f32 v[12:13], v[170:171], v[24:25], v[12:13] op_sel_hi:[0,1,1]
	v_pk_fma_f32 v[14:15], v[170:171], v[26:27], v[14:15] op_sel_hi:[0,1,1]
	ds_read_b128 v[168:171], v176 offset:2176
	global_store_dwordx4 v177, v[24:27], s[16:17] nt
	s_add_u32 s16, s16, 0x800
	s_addc_u32 s17, s17, 0
	s_waitcnt vmcnt(31)
	s_waitcnt lgkmcnt(1)
	v_pk_mul_f32 v[172:173], v[164:165], v[148:149] op_sel:[1,0] op_sel_hi:[1,1]
	v_pk_mul_f32 v[174:175], v[164:165], v[150:151] op_sel:[1,0] op_sel_hi:[1,1]
	v_pk_fma_f32 v[28:29], v[164:165], v[28:29], v[172:173] op_sel_hi:[0,1,1]
	v_pk_fma_f32 v[30:31], v[164:165], v[30:31], v[174:175] op_sel_hi:[0,1,1]
	v_pk_fma_f32 v[0:1], v[166:167], v[28:29], v[0:1] op_sel_hi:[0,1,1]
	v_pk_fma_f32 v[2:3], v[166:167], v[30:31], v[2:3] op_sel_hi:[0,1,1]
	ds_read_b128 v[164:167], v176 offset:4224
	s_waitcnt lgkmcnt(1)
	v_pk_mul_f32 v[172:173], v[168:169], v[152:153] op_sel:[1,0] op_sel_hi:[1,1]
	v_pk_mul_f32 v[174:175], v[168:169], v[154:155] op_sel:[1,0] op_sel_hi:[1,1]
	v_pk_fma_f32 v[28:29], v[168:169], v[28:29], v[172:173] op_sel_hi:[0,1,1]
	v_pk_fma_f32 v[30:31], v[168:169], v[30:31], v[174:175] op_sel_hi:[0,1,1]
	v_pk_fma_f32 v[4:5], v[170:171], v[28:29], v[4:5] op_sel_hi:[0,1,1]
	v_pk_fma_f32 v[6:7], v[170:171], v[30:31], v[6:7] op_sel_hi:[0,1,1]
	ds_read_b128 v[168:171], v176 offset:6272
	s_waitcnt lgkmcnt(1)
	v_pk_mul_f32 v[172:173], v[164:165], v[156:157] op_sel:[1,0] op_sel_hi:[1,1]
	v_pk_mul_f32 v[174:175], v[164:165], v[158:159] op_sel:[1,0] op_sel_hi:[1,1]
	v_pk_fma_f32 v[28:29], v[164:165], v[28:29], v[172:173] op_sel_hi:[0,1,1]
	v_pk_fma_f32 v[30:31], v[164:165], v[30:31], v[174:175] op_sel_hi:[0,1,1]
	v_pk_fma_f32 v[8:9], v[166:167], v[28:29], v[8:9] op_sel_hi:[0,1,1]
	v_pk_fma_f32 v[10:11], v[166:167], v[30:31], v[10:11] op_sel_hi:[0,1,1]
	ds_read_b128 v[164:167], v176 offset:192
	s_waitcnt lgkmcnt(1)
	v_pk_mul_f32 v[172:173], v[168:169], v[160:161] op_sel:[1,0] op_sel_hi:[1,1]
	v_pk_mul_f32 v[174:175], v[168:169], v[162:163] op_sel:[1,0] op_sel_hi:[1,1]
	v_pk_fma_f32 v[28:29], v[168:169], v[28:29], v[172:173] op_sel_hi:[0,1,1]
	v_pk_fma_f32 v[30:31], v[168:169], v[30:31], v[174:175] op_sel_hi:[0,1,1]
	v_pk_fma_f32 v[12:13], v[170:171], v[28:29], v[12:13] op_sel_hi:[0,1,1]
	v_pk_fma_f32 v[14:15], v[170:171], v[30:31], v[14:15] op_sel_hi:[0,1,1]
	ds_read_b128 v[168:171], v176 offset:2240
	global_store_dwordx4 v177, v[28:31], s[16:17] nt
	s_add_u32 s16, s16, 0x800
	s_addc_u32 s17, s17, 0
	s_waitcnt vmcnt(31)
	s_waitcnt lgkmcnt(1)
; #define LAS __attribute__((address_space(3)))
; __device__ __forceinline__ void hgrn_sample_wave(LAS float* buf, const GAS float* Z, const GAS float* logits, int layer, int b, int h, int vh, const GAS float* Sin, GAS float* Sout, GAS bf16* OPB, int lane) {
;     ...
;     for (int dc = 0; dc < 16; ++dc) { float S[8];
; #pragma unroll
;         for (int dd = 0; dd < 8; ++dd) S[dd] = Sn[dd];
;         if (dc + 1 < 16) {
; #pragma unroll
;             for (int dd = 0; dd < 8; ++dd) Sn[dd] = __builtin_nontemporal_load(&Sin[((dc + 1) * 8 + dd) * 128 + vh * 64 + lane]); }
; #pragma unroll
;         for (int t = 0; t < 4; ++t)
; #pragma unroll
;             for (int dd = 0; dd < 8; ++dd) { const f32x4 op = *(const LAS f32x4*)(buf + (t * 128 + dc * 8 + dd) * 4); S[dd] = op.x * S[dd] + op.y * vt[t]; o[t] += op.z * S[dd]; }
; #pragma unroll
;         for (int dd = 0; dd < 8; ++dd) __builtin_nontemporal_store(S[dd], &Sout[(dc * 8 + dd) * 128 + vh * 64 + lane]); }
	v_pk_mul_f32 v[172:173], v[164:165], v[148:149] op_sel:[1,0] op_sel_hi:[1,1]
	v_pk_mul_f32 v[174:175], v[164:165], v[150:151] op_sel:[1,0] op_sel_hi:[1,1]
	v_pk_fma_f32 v[32:33], v[164:165], v[32:33], v[172:173] op_sel_hi:[0,1,1]
	v_pk_fma_f32 v[34:35], v[164:165], v[34:35], v[174:175] op_sel_hi:[0,1,1]
	v_pk_fma_f32 v[0:1], v[166:167], v[32:33], v[0:1] op_sel_hi:[0,1,1]
	v_pk_fma_f32 v[2:3], v[166:167], v[34:35], v[2:3] op_sel_hi:[0,1,1]
	ds_read_b128 v[164:167], v176 offset:4288
	s_waitcnt lgkmcnt(1)
	v_pk_mul_f32 v[172:173], v[168:169], v[152:153] op_sel:[1,0] op_sel_hi:[1,1]
	v_pk_mul_f32 v[174:175], v[168:169], v[154:155] op_sel:[1,0] op_sel_hi:[1,1]
	v_pk_fma_f32 v[32:33], v[168:169], v[32:33], v[172:173] op_sel_hi:[0,1,1]
	v_pk_fma_f32 v[34:35], v[168:169], v[34:35], v[174:175] op_sel_hi:[0,1,1]
	v_pk_fma_f32 v[4:5], v[170:171], v[32:33], v[4:5] op_sel_hi:[0,1,1]
	v_pk_fma_f32 v[6:7], v[170:171], v[34:35], v[6:7] op_sel_hi:[0,1,1]
	ds_read_b128 v[168:171], v176 offset:6336
	s_waitcnt lgkmcnt(1)
	v_pk_mul_f32 v[172:173], v[164:165], v[156:157] op_sel:[1,0] op_sel_hi:[1,1]
	v_pk_mul_f32 v[174:175], v[164:165], v[158:159] op_sel:[1,0] op_sel_hi:[1,1]
	v_pk_fma_f32 v[32:33], v[164:165], v[32:33], v[172:173] op_sel_hi:[0,1,1]
	v_pk_fma_f32 v[34:35], v[164:165], v[34:35], v[174:175] op_sel_hi:[0,1,1]
	v_pk_fma_f32 v[8:9], v[166:167], v[32:33], v[8:9] op_sel_hi:[0,1,1]
	v_pk_fma_f32 v[10:11], v[166:167], v[34:35], v[10:11] op_sel_hi:[0,1,1]
	ds_read_b128 v[164:167], v176 offset:256
	s_waitcnt lgkmcnt(1)
	v_pk_mul_f32 v[172:173], v[168:169], v[160:161] op_sel:[1,0] op_sel_hi:[1,1]
	v_pk_mul_f32 v[174:175], v[168:169], v[162:163] op_sel:[1,0] op_sel_hi:[1,1]
	v_pk_fma_f32 v[32:33], v[168:169], v[32:33], v[172:173] op_sel_hi:[0,1,1]
	v_pk_fma_f32 v[34:35], v[168:169], v[34:35], v[174:175] op_sel_hi:[0,1,1]
	v_pk_fma_f32 v[12:13], v[170:171], v[32:33], v[12:13] op_sel_hi:[0,1,1]
	v_pk_fma_f32 v[14:15], v[170:171], v[34:35], v[14:15] op_sel_hi:[0,1,1]
	ds_read_b128 v[168:171], v176 offset:2304
	global_store_dwordx4 v177, v[32:35], s[16:17] nt
	s_add_u32 s16, s16, 0x800
	s_addc_u32 s17, s17, 0
	s_waitcnt vmcnt(31)
	s_waitcnt lgkmcnt(1)
	v_pk_mul_f32 v[172:173], v[164:165], v[148:149] op_sel:[1,0] op_sel_hi:[1,1]
	v_pk_mul_f32 v[174:175], v[164:165], v[150:151] op_sel:[1,0] op_sel_hi:[1,1]
	v_pk_fma_f32 v[36:37], v[164:165], v[36:37], v[172:173] op_sel_hi:[0,1,1]
	v_pk_fma_f32 v[38:39], v[164:165], v[38:39], v[174:175] op_sel_hi:[0,1,1]
	v_pk_fma_f32 v[0:1], v[166:167], v[36:37], v[0:1] op_sel_hi:[0,1,1]
	v_pk_fma_f32 v[2:3], v[166:167], v[38:39], v[2:3] op_sel_hi:[0,1,1]
	ds_read_b128 v[164:167], v176 offset:4352
	s_waitcnt lgkmcnt(1)
	v_pk_mul_f32 v[172:173], v[168:169], v[152:153] op_sel:[1,0] op_sel_hi:[1,1]
	v_pk_mul_f32 v[174:175], v[168:169], v[154:155] op_sel:[1,0] op_sel_hi:[1,1]
	v_pk_fma_f32 v[36:37], v[168:169], v[36:37], v[172:173] op_sel_hi:[0,1,1]
	v_pk_fma_f32 v[38:39], v[168:169], v[38:39], v[174:175] op_sel_hi:[0,1,1]
	v_pk_fma_f32 v[4:5], v[170:171], v[36:37], v[4:5] op_sel_hi:[0,1,1]
	v_pk_fma_f32 v[6:7], v[170:171], v[38:39], v[6:7] op_sel_hi:[0,1,1]
	ds_read_b128 v[168:171], v176 offset:6400
	s_waitcnt lgkmcnt(1)
	v_pk_mul_f32 v[172:173], v[164:165], v[156:157] op_sel:[1,0] op_sel_hi:[1,1]
	v_pk_mul_f32 v[174:175], v[164:165], v[158:159] op_sel:[1,0] op_sel_hi:[1,1]
	v_pk_fma_f32 v[36:37], v[164:165], v[36:37], v[172:173] op_sel_hi:[0,1,1]
	v_pk_fma_f32 v[38:39], v[164:165], v[38:39], v[174:175] op_sel_hi:[0,1,1]
	v_pk_fma_f32 v[8:9], v[166:167], v[36:37], v[8:9] op_sel_hi:[0,1,1]
	v_pk_fma_f32 v[10:11], v[166:167], v[38:39], v[10:11] op_sel_hi:[0,1,1]
	ds_read_b128 v[164:167], v176 offset:320
	s_waitcnt lgkmcnt(1)
	v_pk_mul_f32 v[172:173], v[168:169], v[160:161] op_sel:[1,0] op_sel_hi:[1,1]
	v_pk_mul_f32 v[174:175], v[168:169], v[162:163] op_sel:[1,0] op_sel_hi:[1,1]
	v_pk_fma_f32 v[36:37], v[168:169], v[36:37], v[172:173] op_sel_hi:[0,1,1]
	v_pk_fma_f32 v[38:39], v[168:169], v[38:39], v[174:175] op_sel_hi:[0,1,1]
	v_pk_fma_f32 v[12:13], v[170:171], v[36:37], v[12:13] op_sel_hi:[0,1,1]
	v_pk_fma_f32 v[14:15], v[170:171], v[38:39], v[14:15] op_sel_hi:[0,1,1]
	ds_read_b128 v[168:171], v176 offset:2368
	global_store_dwordx4 v177, v[36:39], s[16:17] nt
	s_add_u32 s16, s16, 0x800
	s_addc_u32 s17, s17, 0
	s_waitcnt vmcnt(31)
	s_waitcnt lgkmcnt(1)
	v_pk_mul_f32 v[172:173], v[164:165], v[148:149] op_sel:[1,0] op_sel_hi:[1,1]
	v_pk_mul_f32 v[174:175], v[164:165], v[150:151] op_sel:[1,0] op_sel_hi:[1,1]
	v_pk_fma_f32 v[40:41], v[164:165], v[40:41], v[172:173] op_sel_hi:[0,1,1]
	v_pk_fma_f32 v[42:43], v[164:165], v[42:43], v[174:175] op_sel_hi:[0,1,1]
	v_pk_fma_f32 v[0:1], v[166:167], v[40:41], v[0:1] op_sel_hi:[0,1,1]
	v_pk_fma_f32 v[2:3], v[166:167], v[42:43], v[2:3] op_sel_hi:[0,1,1]
	ds_read_b128 v[164:167], v176 offset:4416
	s_waitcnt lgkmcnt(1)
	v_pk_mul_f32 v[172:173], v[168:169], v[152:153] op_sel:[1,0] op_sel_hi:[1,1]
	v_pk_mul_f32 v[174:175], v[168:169], v[154:155] op_sel:[1,0] op_sel_hi:[1,1]
	v_pk_fma_f32 v[40:41], v[168:169], v[40:41], v[172:173] op_sel_hi:[0,1,1]
	v_pk_fma_f32 v[42:43], v[168:169], v[42:43], v[174:175] op_sel_hi:[0,1,1]
	v_pk_fma_f32 v[4:5], v[170:171], v[40:41], v[4:5] op_sel_hi:[0,1,1]
	v_pk_fma_f32 v[6:7], v[170:171], v[42:43], v[6:7] op_sel_hi:[0,1,1]
	ds_read_b128 v[168:171], v176 offset:6464
	s_waitcnt lgkmcnt(1)
	v_pk_mul_f32 v[172:173], v[164:165], v[156:157] op_sel:[1,0] op_sel_hi:[1,1]
	v_pk_mul_f32 v[174:175], v[164:165], v[158:159] op_sel:[1,0] op_sel_hi:[1,1]
	v_pk_fma_f32 v[40:41], v[164:165], v[40:41], v[172:173] op_sel_hi:[0,1,1]
	v_pk_fma_f32 v[42:43], v[164:165], v[42:43], v[174:175] op_sel_hi:[0,1,1]
	v_pk_fma_f32 v[8:9], v[166:167], v[40:41], v[8:9] op_sel_hi:[0,1,1]
	v_pk_fma_f32 v[10:11], v[166:167], v[42:43], v[10:11] op_sel_hi:[0,1,1]
	ds_read_b128 v[164:167], v176 offset:384
	s_waitcnt lgkmcnt(1)
; #define LAS __attribute__((address_space(3)))
; __device__ __forceinline__ void hgrn_sample_wave(LAS float* buf, const GAS float* Z, const GAS float* logits, int layer, int b, int h, int vh, const GAS float* Sin, GAS float* Sout, GAS bf16* OPB, int lane) {
;     ...
;     for (int dc = 0; dc < 16; ++dc) { float S[8];
; #pragma unroll
;         for (int dd = 0; dd < 8; ++dd) S[dd] = Sn[dd];
;         if (dc + 1 < 16) {
; #pragma unroll
;             for (int dd = 0; dd < 8; ++dd) Sn[dd] = __builtin_nontemporal_load(&Sin[((dc + 1) * 8 + dd) * 128 + vh * 64 + lane]); }
; #pragma unroll
;         for (int t = 0; t < 4; ++t)
; #pragma unroll
;             for (int dd = 0; dd < 8; ++dd) { const f32x4 op = *(const LAS f32x4*)(buf + (t * 128 + dc * 8 + dd) * 4); S[dd] = op.x * S[dd] + op.y * vt[t]; o[t] += op.z * S[dd]; }
; #pragma unroll
;         for (int dd = 0; dd < 8; ++dd) __builtin_nontemporal_store(S[dd], &Sout[(dc * 8 + dd) * 128 + vh * 64 + lane]); }
	v_pk_mul_f32 v[172:173], v[168:169], v[160:161] op_sel:[1,0] op_sel_hi:[1,1]
	v_pk_mul_f32 v[174:175], v[168:169], v[162:163] op_sel:[1,0] op_sel_hi:[1,1]
	v_pk_fma_f32 v[40:41], v[168:169], v[40:41], v[172:173] op_sel_hi:[0,1,1]
	v_pk_fma_f32 v[42:43], v[168:169], v[42:43], v[174:175] op_sel_hi:[0,1,1]
	v_pk_fma_f32 v[12:13], v[170:171], v[40:41], v[12:13] op_sel_hi:[0,1,1]
	v_pk_fma_f32 v[14:15], v[170:171], v[42:43], v[14:15] op_sel_hi:[0,1,1]
	ds_read_b128 v[168:171], v176 offset:2432
	global_store_dwordx4 v177, v[40:43], s[16:17] nt
	s_add_u32 s16, s16, 0x800
	s_addc_u32 s17, s17, 0
	s_waitcnt vmcnt(31)
	s_waitcnt lgkmcnt(1)
	v_pk_mul_f32 v[172:173], v[164:165], v[148:149] op_sel:[1,0] op_sel_hi:[1,1]
	v_pk_mul_f32 v[174:175], v[164:165], v[150:151] op_sel:[1,0] op_sel_hi:[1,1]
	v_pk_fma_f32 v[44:45], v[164:165], v[44:45], v[172:173] op_sel_hi:[0,1,1]
	v_pk_fma_f32 v[46:47], v[164:165], v[46:47], v[174:175] op_sel_hi:[0,1,1]
	v_pk_fma_f32 v[0:1], v[166:167], v[44:45], v[0:1] op_sel_hi:[0,1,1]
	v_pk_fma_f32 v[2:3], v[166:167], v[46:47], v[2:3] op_sel_hi:[0,1,1]
	ds_read_b128 v[164:167], v176 offset:4480
	s_waitcnt lgkmcnt(1)
	v_pk_mul_f32 v[172:173], v[168:169], v[152:153] op_sel:[1,0] op_sel_hi:[1,1]
	v_pk_mul_f32 v[174:175], v[168:169], v[154:155] op_sel:[1,0] op_sel_hi:[1,1]
	v_pk_fma_f32 v[44:45], v[168:169], v[44:45], v[172:173] op_sel_hi:[0,1,1]
	v_pk_fma_f32 v[46:47], v[168:169], v[46:47], v[174:175] op_sel_hi:[0,1,1]
	v_pk_fma_f32 v[4:5], v[170:171], v[44:45], v[4:5] op_sel_hi:[0,1,1]
	v_pk_fma_f32 v[6:7], v[170:171], v[46:47], v[6:7] op_sel_hi:[0,1,1]
	ds_read_b128 v[168:171], v176 offset:6528
	s_waitcnt lgkmcnt(1)
	v_pk_mul_f32 v[172:173], v[164:165], v[156:157] op_sel:[1,0] op_sel_hi:[1,1]
	v_pk_mul_f32 v[174:175], v[164:165], v[158:159] op_sel:[1,0] op_sel_hi:[1,1]
	v_pk_fma_f32 v[44:45], v[164:165], v[44:45], v[172:173] op_sel_hi:[0,1,1]
	v_pk_fma_f32 v[46:47], v[164:165], v[46:47], v[174:175] op_sel_hi:[0,1,1]
	v_pk_fma_f32 v[8:9], v[166:167], v[44:45], v[8:9] op_sel_hi:[0,1,1]
	v_pk_fma_f32 v[10:11], v[166:167], v[46:47], v[10:11] op_sel_hi:[0,1,1]
	ds_read_b128 v[164:167], v176 offset:448
	s_waitcnt lgkmcnt(1)
	v_pk_mul_f32 v[172:173], v[168:169], v[160:161] op_sel:[1,0] op_sel_hi:[1,1]
	v_pk_mul_f32 v[174:175], v[168:169], v[162:163] op_sel:[1,0] op_sel_hi:[1,1]
	v_pk_fma_f32 v[44:45], v[168:169], v[44:45], v[172:173] op_sel_hi:[0,1,1]
	v_pk_fma_f32 v[46:47], v[168:169], v[46:47], v[174:175] op_sel_hi:[0,1,1]
	v_pk_fma_f32 v[12:13], v[170:171], v[44:45], v[12:13] op_sel_hi:[0,1,1]
	v_pk_fma_f32 v[14:15], v[170:171], v[46:47], v[14:15] op_sel_hi:[0,1,1]
	ds_read_b128 v[168:171], v176 offset:2496
	global_store_dwordx4 v177, v[44:47], s[16:17] nt
	s_add_u32 s16, s16, 0x800
	s_addc_u32 s17, s17, 0
	s_waitcnt vmcnt(31)
	s_waitcnt lgkmcnt(1)
	v_pk_mul_f32 v[172:173], v[164:165], v[148:149] op_sel:[1,0] op_sel_hi:[1,1]
	v_pk_mul_f32 v[174:175], v[164:165], v[150:151] op_sel:[1,0] op_sel_hi:[1,1]
	v_pk_fma_f32 v[48:49], v[164:165], v[48:49], v[172:173] op_sel_hi:[0,1,1]
	v_pk_fma_f32 v[50:51], v[164:165], v[50:51], v[174:175] op_sel_hi:[0,1,1]
	v_pk_fma_f32 v[0:1], v[166:167], v[48:49], v[0:1] op_sel_hi:[0,1,1]
	v_pk_fma_f32 v[2:3], v[166:167], v[50:51], v[2:3] op_sel_hi:[0,1,1]
	ds_read_b128 v[164:167], v176 offset:4544
	s_waitcnt lgkmcnt(1)
	v_pk_mul_f32 v[172:173], v[168:169], v[152:153] op_sel:[1,0] op_sel_hi:[1,1]
	v_pk_mul_f32 v[174:175], v[168:169], v[154:155] op_sel:[1,0] op_sel_hi:[1,1]
	v_pk_fma_f32 v[48:49], v[168:169], v[48:49], v[172:173] op_sel_hi:[0,1,1]
	v_pk_fma_f32 v[50:51], v[168:169], v[50:51], v[174:175] op_sel_hi:[0,1,1]
	v_pk_fma_f32 v[4:5], v[170:171], v[48:49], v[4:5] op_sel_hi:[0,1,1]
	v_pk_fma_f32 v[6:7], v[170:171], v[50:51], v[6:7] op_sel_hi:[0,1,1]
	ds_read_b128 v[168:171], v176 offset:6592
	s_waitcnt lgkmcnt(1)
	v_pk_mul_f32 v[172:173], v[164:165], v[156:157] op_sel:[1,0] op_sel_hi:[1,1]
	v_pk_mul_f32 v[174:175], v[164:165], v[158:159] op_sel:[1,0] op_sel_hi:[1,1]
	v_pk_fma_f32 v[48:49], v[164:165], v[48:49], v[172:173] op_sel_hi:[0,1,1]
	v_pk_fma_f32 v[50:51], v[164:165], v[50:51], v[174:175] op_sel_hi:[0,1,1]
	v_pk_fma_f32 v[8:9], v[166:167], v[48:49], v[8:9] op_sel_hi:[0,1,1]
	v_pk_fma_f32 v[10:11], v[166:167], v[50:51], v[10:11] op_sel_hi:[0,1,1]
	ds_read_b128 v[164:167], v176 offset:512
	s_waitcnt lgkmcnt(1)
	v_pk_mul_f32 v[172:173], v[168:169], v[160:161] op_sel:[1,0] op_sel_hi:[1,1]
	v_pk_mul_f32 v[174:175], v[168:169], v[162:163] op_sel:[1,0] op_sel_hi:[1,1]
	v_pk_fma_f32 v[48:49], v[168:169], v[48:49], v[172:173] op_sel_hi:[0,1,1]
	v_pk_fma_f32 v[50:51], v[168:169], v[50:51], v[174:175] op_sel_hi:[0,1,1]
	v_pk_fma_f32 v[12:13], v[170:171], v[48:49], v[12:13] op_sel_hi:[0,1,1]
	v_pk_fma_f32 v[14:15], v[170:171], v[50:51], v[14:15] op_sel_hi:[0,1,1]
	ds_read_b128 v[168:171], v176 offset:2560
	global_store_dwordx4 v177, v[48:51], s[16:17] nt
	s_add_u32 s16, s16, 0x800
	s_addc_u32 s17, s17, 0
	s_waitcnt vmcnt(31)
	s_waitcnt lgkmcnt(1)
	v_pk_mul_f32 v[172:173], v[164:165], v[148:149] op_sel:[1,0] op_sel_hi:[1,1]
	v_pk_mul_f32 v[174:175], v[164:165], v[150:151] op_sel:[1,0] op_sel_hi:[1,1]
	v_pk_fma_f32 v[52:53], v[164:165], v[52:53], v[172:173] op_sel_hi:[0,1,1]
	v_pk_fma_f32 v[54:55], v[164:165], v[54:55], v[174:175] op_sel_hi:[0,1,1]
	v_pk_fma_f32 v[0:1], v[166:167], v[52:53], v[0:1] op_sel_hi:[0,1,1]
	v_pk_fma_f32 v[2:3], v[166:167], v[54:55], v[2:3] op_sel_hi:[0,1,1]
	ds_read_b128 v[164:167], v176 offset:4608
	s_waitcnt lgkmcnt(1)
; #define LAS __attribute__((address_space(3)))
; __device__ __forceinline__ void hgrn_sample_wave(LAS float* buf, const GAS float* Z, const GAS float* logits, int layer, int b, int h, int vh, const GAS float* Sin, GAS float* Sout, GAS bf16* OPB, int lane) {
;     ...
;     for (int dc = 0; dc < 16; ++dc) { float S[8];
; #pragma unroll
;         for (int dd = 0; dd < 8; ++dd) S[dd] = Sn[dd];
;         if (dc + 1 < 16) {
; #pragma unroll
;             for (int dd = 0; dd < 8; ++dd) Sn[dd] = __builtin_nontemporal_load(&Sin[((dc + 1) * 8 + dd) * 128 + vh * 64 + lane]); }
; #pragma unroll
;         for (int t = 0; t < 4; ++t)
; #pragma unroll
;             for (int dd = 0; dd < 8; ++dd) { const f32x4 op = *(const LAS f32x4*)(buf + (t * 128 + dc * 8 + dd) * 4); S[dd] = op.x * S[dd] + op.y * vt[t]; o[t] += op.z * S[dd]; }
; #pragma unroll
;         for (int dd = 0; dd < 8; ++dd) __builtin_nontemporal_store(S[dd], &Sout[(dc * 8 + dd) * 128 + vh * 64 + lane]); }
	v_pk_mul_f32 v[172:173], v[168:169], v[152:153] op_sel:[1,0] op_sel_hi:[1,1]
	v_pk_mul_f32 v[174:175], v[168:169], v[154:155] op_sel:[1,0] op_sel_hi:[1,1]
	v_pk_fma_f32 v[52:53], v[168:169], v[52:53], v[172:173] op_sel_hi:[0,1,1]
	v_pk_fma_f32 v[54:55], v[168:169], v[54:55], v[174:175] op_sel_hi:[0,1,1]
	v_pk_fma_f32 v[4:5], v[170:171], v[52:53], v[4:5] op_sel_hi:[0,1,1]
	v_pk_fma_f32 v[6:7], v[170:171], v[54:55], v[6:7] op_sel_hi:[0,1,1]
	ds_read_b128 v[168:171], v176 offset:6656
	s_waitcnt lgkmcnt(1)
	v_pk_mul_f32 v[172:173], v[164:165], v[156:157] op_sel:[1,0] op_sel_hi:[1,1]
	v_pk_mul_f32 v[174:175], v[164:165], v[158:159] op_sel:[1,0] op_sel_hi:[1,1]
	v_pk_fma_f32 v[52:53], v[164:165], v[52:53], v[172:173] op_sel_hi:[0,1,1]
	v_pk_fma_f32 v[54:55], v[164:165], v[54:55], v[174:175] op_sel_hi:[0,1,1]
	v_pk_fma_f32 v[8:9], v[166:167], v[52:53], v[8:9] op_sel_hi:[0,1,1]
	v_pk_fma_f32 v[10:11], v[166:167], v[54:55], v[10:11] op_sel_hi:[0,1,1]
	ds_read_b128 v[164:167], v176 offset:576
	s_waitcnt lgkmcnt(1)
	v_pk_mul_f32 v[172:173], v[168:169], v[160:161] op_sel:[1,0] op_sel_hi:[1,1]
	v_pk_mul_f32 v[174:175], v[168:169], v[162:163] op_sel:[1,0] op_sel_hi:[1,1]
	v_pk_fma_f32 v[52:53], v[168:169], v[52:53], v[172:173] op_sel_hi:[0,1,1]
	v_pk_fma_f32 v[54:55], v[168:169], v[54:55], v[174:175] op_sel_hi:[0,1,1]
	v_pk_fma_f32 v[12:13], v[170:171], v[52:53], v[12:13] op_sel_hi:[0,1,1]
	v_pk_fma_f32 v[14:15], v[170:171], v[54:55], v[14:15] op_sel_hi:[0,1,1]
	ds_read_b128 v[168:171], v176 offset:2624
	global_store_dwordx4 v177, v[52:55], s[16:17] nt
	s_add_u32 s16, s16, 0x800
	s_addc_u32 s17, s17, 0
	s_waitcnt vmcnt(31)
	s_waitcnt lgkmcnt(1)
	v_pk_mul_f32 v[172:173], v[164:165], v[148:149] op_sel:[1,0] op_sel_hi:[1,1]
	v_pk_mul_f32 v[174:175], v[164:165], v[150:151] op_sel:[1,0] op_sel_hi:[1,1]
	v_pk_fma_f32 v[56:57], v[164:165], v[56:57], v[172:173] op_sel_hi:[0,1,1]
	v_pk_fma_f32 v[58:59], v[164:165], v[58:59], v[174:175] op_sel_hi:[0,1,1]
	v_pk_fma_f32 v[0:1], v[166:167], v[56:57], v[0:1] op_sel_hi:[0,1,1]
	v_pk_fma_f32 v[2:3], v[166:167], v[58:59], v[2:3] op_sel_hi:[0,1,1]
	ds_read_b128 v[164:167], v176 offset:4672
	s_waitcnt lgkmcnt(1)
	v_pk_mul_f32 v[172:173], v[168:169], v[152:153] op_sel:[1,0] op_sel_hi:[1,1]
	v_pk_mul_f32 v[174:175], v[168:169], v[154:155] op_sel:[1,0] op_sel_hi:[1,1]
	v_pk_fma_f32 v[56:57], v[168:169], v[56:57], v[172:173] op_sel_hi:[0,1,1]
	v_pk_fma_f32 v[58:59], v[168:169], v[58:59], v[174:175] op_sel_hi:[0,1,1]
	v_pk_fma_f32 v[4:5], v[170:171], v[56:57], v[4:5] op_sel_hi:[0,1,1]
	v_pk_fma_f32 v[6:7], v[170:171], v[58:59], v[6:7] op_sel_hi:[0,1,1]
	ds_read_b128 v[168:171], v176 offset:6720
	s_waitcnt lgkmcnt(1)
	v_pk_mul_f32 v[172:173], v[164:165], v[156:157] op_sel:[1,0] op_sel_hi:[1,1]
	v_pk_mul_f32 v[174:175], v[164:165], v[158:159] op_sel:[1,0] op_sel_hi:[1,1]
	v_pk_fma_f32 v[56:57], v[164:165], v[56:57], v[172:173] op_sel_hi:[0,1,1]
	v_pk_fma_f32 v[58:59], v[164:165], v[58:59], v[174:175] op_sel_hi:[0,1,1]
	v_pk_fma_f32 v[8:9], v[166:167], v[56:57], v[8:9] op_sel_hi:[0,1,1]
	v_pk_fma_f32 v[10:11], v[166:167], v[58:59], v[10:11] op_sel_hi:[0,1,1]
	ds_read_b128 v[164:167], v176 offset:640
	s_waitcnt lgkmcnt(1)
	v_pk_mul_f32 v[172:173], v[168:169], v[160:161] op_sel:[1,0] op_sel_hi:[1,1]
	v_pk_mul_f32 v[174:175], v[168:169], v[162:163] op_sel:[1,0] op_sel_hi:[1,1]
	v_pk_fma_f32 v[56:57], v[168:169], v[56:57], v[172:173] op_sel_hi:[0,1,1]
	v_pk_fma_f32 v[58:59], v[168:169], v[58:59], v[174:175] op_sel_hi:[0,1,1]
	v_pk_fma_f32 v[12:13], v[170:171], v[56:57], v[12:13] op_sel_hi:[0,1,1]
	v_pk_fma_f32 v[14:15], v[170:171], v[58:59], v[14:15] op_sel_hi:[0,1,1]
	ds_read_b128 v[168:171], v176 offset:2688
	global_store_dwordx4 v177, v[56:59], s[16:17] nt
	s_add_u32 s16, s16, 0x800
	s_addc_u32 s17, s17, 0
	s_waitcnt vmcnt(31)
	s_waitcnt lgkmcnt(1)
	v_pk_mul_f32 v[172:173], v[164:165], v[148:149] op_sel:[1,0] op_sel_hi:[1,1]
	v_pk_mul_f32 v[174:175], v[164:165], v[150:151] op_sel:[1,0] op_sel_hi:[1,1]
	v_pk_fma_f32 v[60:61], v[164:165], v[60:61], v[172:173] op_sel_hi:[0,1,1]
	v_pk_fma_f32 v[62:63], v[164:165], v[62:63], v[174:175] op_sel_hi:[0,1,1]
	v_pk_fma_f32 v[0:1], v[166:167], v[60:61], v[0:1] op_sel_hi:[0,1,1]
	v_pk_fma_f32 v[2:3], v[166:167], v[62:63], v[2:3] op_sel_hi:[0,1,1]
	ds_read_b128 v[164:167], v176 offset:4736
	s_waitcnt lgkmcnt(1)
	v_pk_mul_f32 v[172:173], v[168:169], v[152:153] op_sel:[1,0] op_sel_hi:[1,1]
	v_pk_mul_f32 v[174:175], v[168:169], v[154:155] op_sel:[1,0] op_sel_hi:[1,1]
	v_pk_fma_f32 v[60:61], v[168:169], v[60:61], v[172:173] op_sel_hi:[0,1,1]
	v_pk_fma_f32 v[62:63], v[168:169], v[62:63], v[174:175] op_sel_hi:[0,1,1]
	v_pk_fma_f32 v[4:5], v[170:171], v[60:61], v[4:5] op_sel_hi:[0,1,1]
	v_pk_fma_f32 v[6:7], v[170:171], v[62:63], v[6:7] op_sel_hi:[0,1,1]
	ds_read_b128 v[168:171], v176 offset:6784
	s_waitcnt lgkmcnt(1)
	v_pk_mul_f32 v[172:173], v[164:165], v[156:157] op_sel:[1,0] op_sel_hi:[1,1]
	v_pk_mul_f32 v[174:175], v[164:165], v[158:159] op_sel:[1,0] op_sel_hi:[1,1]
	v_pk_fma_f32 v[60:61], v[164:165], v[60:61], v[172:173] op_sel_hi:[0,1,1]
	v_pk_fma_f32 v[62:63], v[164:165], v[62:63], v[174:175] op_sel_hi:[0,1,1]
	v_pk_fma_f32 v[8:9], v[166:167], v[60:61], v[8:9] op_sel_hi:[0,1,1]
	v_pk_fma_f32 v[10:11], v[166:167], v[62:63], v[10:11] op_sel_hi:[0,1,1]
	ds_read_b128 v[164:167], v176 offset:704
	s_waitcnt lgkmcnt(1)
; #define LAS __attribute__((address_space(3)))
; __device__ __forceinline__ void hgrn_sample_wave(LAS float* buf, const GAS float* Z, const GAS float* logits, int layer, int b, int h, int vh, const GAS float* Sin, GAS float* Sout, GAS bf16* OPB, int lane) {
;     ...
;     for (int dc = 0; dc < 16; ++dc) { float S[8];
; #pragma unroll
;         for (int dd = 0; dd < 8; ++dd) S[dd] = Sn[dd];
;         if (dc + 1 < 16) {
; #pragma unroll
;             for (int dd = 0; dd < 8; ++dd) Sn[dd] = __builtin_nontemporal_load(&Sin[((dc + 1) * 8 + dd) * 128 + vh * 64 + lane]); }
; #pragma unroll
;         for (int t = 0; t < 4; ++t)
; #pragma unroll
;             for (int dd = 0; dd < 8; ++dd) { const f32x4 op = *(const LAS f32x4*)(buf + (t * 128 + dc * 8 + dd) * 4); S[dd] = op.x * S[dd] + op.y * vt[t]; o[t] += op.z * S[dd]; }
; #pragma unroll
;         for (int dd = 0; dd < 8; ++dd) __builtin_nontemporal_store(S[dd], &Sout[(dc * 8 + dd) * 128 + vh * 64 + lane]); }
	v_pk_mul_f32 v[172:173], v[168:169], v[160:161] op_sel:[1,0] op_sel_hi:[1,1]
	v_pk_mul_f32 v[174:175], v[168:169], v[162:163] op_sel:[1,0] op_sel_hi:[1,1]
	v_pk_fma_f32 v[60:61], v[168:169], v[60:61], v[172:173] op_sel_hi:[0,1,1]
	v_pk_fma_f32 v[62:63], v[168:169], v[62:63], v[174:175] op_sel_hi:[0,1,1]
	v_pk_fma_f32 v[12:13], v[170:171], v[60:61], v[12:13] op_sel_hi:[0,1,1]
	v_pk_fma_f32 v[14:15], v[170:171], v[62:63], v[14:15] op_sel_hi:[0,1,1]
	ds_read_b128 v[168:171], v176 offset:2752
	global_store_dwordx4 v177, v[60:63], s[16:17] nt
	s_add_u32 s16, s16, 0x800
	s_addc_u32 s17, s17, 0
	s_waitcnt vmcnt(31)
	s_waitcnt lgkmcnt(1)
	v_pk_mul_f32 v[172:173], v[164:165], v[148:149] op_sel:[1,0] op_sel_hi:[1,1]
	v_pk_mul_f32 v[174:175], v[164:165], v[150:151] op_sel:[1,0] op_sel_hi:[1,1]
	v_pk_fma_f32 v[64:65], v[164:165], v[64:65], v[172:173] op_sel_hi:[0,1,1]
	v_pk_fma_f32 v[66:67], v[164:165], v[66:67], v[174:175] op_sel_hi:[0,1,1]
	v_pk_fma_f32 v[0:1], v[166:167], v[64:65], v[0:1] op_sel_hi:[0,1,1]
	v_pk_fma_f32 v[2:3], v[166:167], v[66:67], v[2:3] op_sel_hi:[0,1,1]
	ds_read_b128 v[164:167], v176 offset:4800
	s_waitcnt lgkmcnt(1)
	v_pk_mul_f32 v[172:173], v[168:169], v[152:153] op_sel:[1,0] op_sel_hi:[1,1]
	v_pk_mul_f32 v[174:175], v[168:169], v[154:155] op_sel:[1,0] op_sel_hi:[1,1]
	v_pk_fma_f32 v[64:65], v[168:169], v[64:65], v[172:173] op_sel_hi:[0,1,1]
	v_pk_fma_f32 v[66:67], v[168:169], v[66:67], v[174:175] op_sel_hi:[0,1,1]
	v_pk_fma_f32 v[4:5], v[170:171], v[64:65], v[4:5] op_sel_hi:[0,1,1]
	v_pk_fma_f32 v[6:7], v[170:171], v[66:67], v[6:7] op_sel_hi:[0,1,1]
	ds_read_b128 v[168:171], v176 offset:6848
	s_waitcnt lgkmcnt(1)
	v_pk_mul_f32 v[172:173], v[164:165], v[156:157] op_sel:[1,0] op_sel_hi:[1,1]
	v_pk_mul_f32 v[174:175], v[164:165], v[158:159] op_sel:[1,0] op_sel_hi:[1,1]
	v_pk_fma_f32 v[64:65], v[164:165], v[64:65], v[172:173] op_sel_hi:[0,1,1]
	v_pk_fma_f32 v[66:67], v[164:165], v[66:67], v[174:175] op_sel_hi:[0,1,1]
	v_pk_fma_f32 v[8:9], v[166:167], v[64:65], v[8:9] op_sel_hi:[0,1,1]
	v_pk_fma_f32 v[10:11], v[166:167], v[66:67], v[10:11] op_sel_hi:[0,1,1]
	ds_read_b128 v[164:167], v176 offset:768
	s_waitcnt lgkmcnt(1)
	v_pk_mul_f32 v[172:173], v[168:169], v[160:161] op_sel:[1,0] op_sel_hi:[1,1]
	v_pk_mul_f32 v[174:175], v[168:169], v[162:163] op_sel:[1,0] op_sel_hi:[1,1]
	v_pk_fma_f32 v[64:65], v[168:169], v[64:65], v[172:173] op_sel_hi:[0,1,1]
	v_pk_fma_f32 v[66:67], v[168:169], v[66:67], v[174:175] op_sel_hi:[0,1,1]
	v_pk_fma_f32 v[12:13], v[170:171], v[64:65], v[12:13] op_sel_hi:[0,1,1]
	v_pk_fma_f32 v[14:15], v[170:171], v[66:67], v[14:15] op_sel_hi:[0,1,1]
	ds_read_b128 v[168:171], v176 offset:2816
	global_store_dwordx4 v177, v[64:67], s[16:17] nt
	s_add_u32 s16, s16, 0x800
	s_addc_u32 s17, s17, 0
	s_waitcnt vmcnt(31)
	s_waitcnt lgkmcnt(1)
	v_pk_mul_f32 v[172:173], v[164:165], v[148:149] op_sel:[1,0] op_sel_hi:[1,1]
	v_pk_mul_f32 v[174:175], v[164:165], v[150:151] op_sel:[1,0] op_sel_hi:[1,1]
	v_pk_fma_f32 v[68:69], v[164:165], v[68:69], v[172:173] op_sel_hi:[0,1,1]
	v_pk_fma_f32 v[70:71], v[164:165], v[70:71], v[174:175] op_sel_hi:[0,1,1]
	v_pk_fma_f32 v[0:1], v[166:167], v[68:69], v[0:1] op_sel_hi:[0,1,1]
	v_pk_fma_f32 v[2:3], v[166:167], v[70:71], v[2:3] op_sel_hi:[0,1,1]
	ds_read_b128 v[164:167], v176 offset:4864
	s_waitcnt lgkmcnt(1)
	v_pk_mul_f32 v[172:173], v[168:169], v[152:153] op_sel:[1,0] op_sel_hi:[1,1]
	v_pk_mul_f32 v[174:175], v[168:169], v[154:155] op_sel:[1,0] op_sel_hi:[1,1]
	v_pk_fma_f32 v[68:69], v[168:169], v[68:69], v[172:173] op_sel_hi:[0,1,1]
	v_pk_fma_f32 v[70:71], v[168:169], v[70:71], v[174:175] op_sel_hi:[0,1,1]
	v_pk_fma_f32 v[4:5], v[170:171], v[68:69], v[4:5] op_sel_hi:[0,1,1]
	v_pk_fma_f32 v[6:7], v[170:171], v[70:71], v[6:7] op_sel_hi:[0,1,1]
	ds_read_b128 v[168:171], v176 offset:6912
	s_waitcnt lgkmcnt(1)
	v_pk_mul_f32 v[172:173], v[164:165], v[156:157] op_sel:[1,0] op_sel_hi:[1,1]
	v_pk_mul_f32 v[174:175], v[164:165], v[158:159] op_sel:[1,0] op_sel_hi:[1,1]
	v_pk_fma_f32 v[68:69], v[164:165], v[68:69], v[172:173] op_sel_hi:[0,1,1]
	v_pk_fma_f32 v[70:71], v[164:165], v[70:71], v[174:175] op_sel_hi:[0,1,1]
	v_pk_fma_f32 v[8:9], v[166:167], v[68:69], v[8:9] op_sel_hi:[0,1,1]
	v_pk_fma_f32 v[10:11], v[166:167], v[70:71], v[10:11] op_sel_hi:[0,1,1]
	ds_read_b128 v[164:167], v176 offset:832
	s_waitcnt lgkmcnt(1)
	v_pk_mul_f32 v[172:173], v[168:169], v[160:161] op_sel:[1,0] op_sel_hi:[1,1]
	v_pk_mul_f32 v[174:175], v[168:169], v[162:163] op_sel:[1,0] op_sel_hi:[1,1]
	v_pk_fma_f32 v[68:69], v[168:169], v[68:69], v[172:173] op_sel_hi:[0,1,1]
	v_pk_fma_f32 v[70:71], v[168:169], v[70:71], v[174:175] op_sel_hi:[0,1,1]
	v_pk_fma_f32 v[12:13], v[170:171], v[68:69], v[12:13] op_sel_hi:[0,1,1]
	v_pk_fma_f32 v[14:15], v[170:171], v[70:71], v[14:15] op_sel_hi:[0,1,1]
	ds_read_b128 v[168:171], v176 offset:2880
	global_store_dwordx4 v177, v[68:71], s[16:17] nt
	s_add_u32 s16, s16, 0x800
	s_addc_u32 s17, s17, 0
	s_waitcnt vmcnt(31)
	s_waitcnt lgkmcnt(1)
	v_pk_mul_f32 v[172:173], v[164:165], v[148:149] op_sel:[1,0] op_sel_hi:[1,1]
	v_pk_mul_f32 v[174:175], v[164:165], v[150:151] op_sel:[1,0] op_sel_hi:[1,1]
	v_pk_fma_f32 v[72:73], v[164:165], v[72:73], v[172:173] op_sel_hi:[0,1,1]
	v_pk_fma_f32 v[74:75], v[164:165], v[74:75], v[174:175] op_sel_hi:[0,1,1]
	v_pk_fma_f32 v[0:1], v[166:167], v[72:73], v[0:1] op_sel_hi:[0,1,1]
	v_pk_fma_f32 v[2:3], v[166:167], v[74:75], v[2:3] op_sel_hi:[0,1,1]
	ds_read_b128 v[164:167], v176 offset:4928
	s_waitcnt lgkmcnt(1)
; #define LAS __attribute__((address_space(3)))
; __device__ __forceinline__ void hgrn_sample_wave(LAS float* buf, const GAS float* Z, const GAS float* logits, int layer, int b, int h, int vh, const GAS float* Sin, GAS float* Sout, GAS bf16* OPB, int lane) {
;     ...
;     for (int dc = 0; dc < 16; ++dc) { float S[8];
; #pragma unroll
;         for (int dd = 0; dd < 8; ++dd) S[dd] = Sn[dd];
;         if (dc + 1 < 16) {
; #pragma unroll
;             for (int dd = 0; dd < 8; ++dd) Sn[dd] = __builtin_nontemporal_load(&Sin[((dc + 1) * 8 + dd) * 128 + vh * 64 + lane]); }
; #pragma unroll
;         for (int t = 0; t < 4; ++t)
; #pragma unroll
;             for (int dd = 0; dd < 8; ++dd) { const f32x4 op = *(const LAS f32x4*)(buf + (t * 128 + dc * 8 + dd) * 4); S[dd] = op.x * S[dd] + op.y * vt[t]; o[t] += op.z * S[dd]; }
; #pragma unroll
;         for (int dd = 0; dd < 8; ++dd) __builtin_nontemporal_store(S[dd], &Sout[(dc * 8 + dd) * 128 + vh * 64 + lane]); }
	v_pk_mul_f32 v[172:173], v[168:169], v[152:153] op_sel:[1,0] op_sel_hi:[1,1]
	v_pk_mul_f32 v[174:175], v[168:169], v[154:155] op_sel:[1,0] op_sel_hi:[1,1]
	v_pk_fma_f32 v[72:73], v[168:169], v[72:73], v[172:173] op_sel_hi:[0,1,1]
	v_pk_fma_f32 v[74:75], v[168:169], v[74:75], v[174:175] op_sel_hi:[0,1,1]
	v_pk_fma_f32 v[4:5], v[170:171], v[72:73], v[4:5] op_sel_hi:[0,1,1]
	v_pk_fma_f32 v[6:7], v[170:171], v[74:75], v[6:7] op_sel_hi:[0,1,1]
	ds_read_b128 v[168:171], v176 offset:6976
	s_waitcnt lgkmcnt(1)
	v_pk_mul_f32 v[172:173], v[164:165], v[156:157] op_sel:[1,0] op_sel_hi:[1,1]
	v_pk_mul_f32 v[174:175], v[164:165], v[158:159] op_sel:[1,0] op_sel_hi:[1,1]
	v_pk_fma_f32 v[72:73], v[164:165], v[72:73], v[172:173] op_sel_hi:[0,1,1]
	v_pk_fma_f32 v[74:75], v[164:165], v[74:75], v[174:175] op_sel_hi:[0,1,1]
	v_pk_fma_f32 v[8:9], v[166:167], v[72:73], v[8:9] op_sel_hi:[0,1,1]
	v_pk_fma_f32 v[10:11], v[166:167], v[74:75], v[10:11] op_sel_hi:[0,1,1]
	ds_read_b128 v[164:167], v176 offset:896
	s_waitcnt lgkmcnt(1)
	v_pk_mul_f32 v[172:173], v[168:169], v[160:161] op_sel:[1,0] op_sel_hi:[1,1]
	v_pk_mul_f32 v[174:175], v[168:169], v[162:163] op_sel:[1,0] op_sel_hi:[1,1]
	v_pk_fma_f32 v[72:73], v[168:169], v[72:73], v[172:173] op_sel_hi:[0,1,1]
	v_pk_fma_f32 v[74:75], v[168:169], v[74:75], v[174:175] op_sel_hi:[0,1,1]
	v_pk_fma_f32 v[12:13], v[170:171], v[72:73], v[12:13] op_sel_hi:[0,1,1]
	v_pk_fma_f32 v[14:15], v[170:171], v[74:75], v[14:15] op_sel_hi:[0,1,1]
	ds_read_b128 v[168:171], v176 offset:2944
	global_store_dwordx4 v177, v[72:75], s[16:17] nt
	s_add_u32 s16, s16, 0x800
	s_addc_u32 s17, s17, 0
	s_waitcnt vmcnt(31)
	s_waitcnt lgkmcnt(1)
	v_pk_mul_f32 v[172:173], v[164:165], v[148:149] op_sel:[1,0] op_sel_hi:[1,1]
	v_pk_mul_f32 v[174:175], v[164:165], v[150:151] op_sel:[1,0] op_sel_hi:[1,1]
	v_pk_fma_f32 v[76:77], v[164:165], v[76:77], v[172:173] op_sel_hi:[0,1,1]
	v_pk_fma_f32 v[78:79], v[164:165], v[78:79], v[174:175] op_sel_hi:[0,1,1]
	v_pk_fma_f32 v[0:1], v[166:167], v[76:77], v[0:1] op_sel_hi:[0,1,1]
	v_pk_fma_f32 v[2:3], v[166:167], v[78:79], v[2:3] op_sel_hi:[0,1,1]
	ds_read_b128 v[164:167], v176 offset:4992
	s_waitcnt lgkmcnt(1)
	v_pk_mul_f32 v[172:173], v[168:169], v[152:153] op_sel:[1,0] op_sel_hi:[1,1]
	v_pk_mul_f32 v[174:175], v[168:169], v[154:155] op_sel:[1,0] op_sel_hi:[1,1]
	v_pk_fma_f32 v[76:77], v[168:169], v[76:77], v[172:173] op_sel_hi:[0,1,1]
	v_pk_fma_f32 v[78:79], v[168:169], v[78:79], v[174:175] op_sel_hi:[0,1,1]
	v_pk_fma_f32 v[4:5], v[170:171], v[76:77], v[4:5] op_sel_hi:[0,1,1]
	v_pk_fma_f32 v[6:7], v[170:171], v[78:79], v[6:7] op_sel_hi:[0,1,1]
	ds_read_b128 v[168:171], v176 offset:7040
	s_waitcnt lgkmcnt(1)
	v_pk_mul_f32 v[172:173], v[164:165], v[156:157] op_sel:[1,0] op_sel_hi:[1,1]
	v_pk_mul_f32 v[174:175], v[164:165], v[158:159] op_sel:[1,0] op_sel_hi:[1,1]
	v_pk_fma_f32 v[76:77], v[164:165], v[76:77], v[172:173] op_sel_hi:[0,1,1]
	v_pk_fma_f32 v[78:79], v[164:165], v[78:79], v[174:175] op_sel_hi:[0,1,1]
	v_pk_fma_f32 v[8:9], v[166:167], v[76:77], v[8:9] op_sel_hi:[0,1,1]
	v_pk_fma_f32 v[10:11], v[166:167], v[78:79], v[10:11] op_sel_hi:[0,1,1]
	ds_read_b128 v[164:167], v176 offset:960
	s_waitcnt lgkmcnt(1)
	v_pk_mul_f32 v[172:173], v[168:169], v[160:161] op_sel:[1,0] op_sel_hi:[1,1]
	v_pk_mul_f32 v[174:175], v[168:169], v[162:163] op_sel:[1,0] op_sel_hi:[1,1]
	v_pk_fma_f32 v[76:77], v[168:169], v[76:77], v[172:173] op_sel_hi:[0,1,1]
	v_pk_fma_f32 v[78:79], v[168:169], v[78:79], v[174:175] op_sel_hi:[0,1,1]
	v_pk_fma_f32 v[12:13], v[170:171], v[76:77], v[12:13] op_sel_hi:[0,1,1]
	v_pk_fma_f32 v[14:15], v[170:171], v[78:79], v[14:15] op_sel_hi:[0,1,1]
	ds_read_b128 v[168:171], v176 offset:3008
	global_store_dwordx4 v177, v[76:79], s[16:17] nt
	s_add_u32 s16, s16, 0x800
	s_addc_u32 s17, s17, 0
	s_waitcnt vmcnt(31)
	s_waitcnt lgkmcnt(1)
	v_pk_mul_f32 v[172:173], v[164:165], v[148:149] op_sel:[1,0] op_sel_hi:[1,1]
	v_pk_mul_f32 v[174:175], v[164:165], v[150:151] op_sel:[1,0] op_sel_hi:[1,1]
	v_pk_fma_f32 v[80:81], v[164:165], v[80:81], v[172:173] op_sel_hi:[0,1,1]
	v_pk_fma_f32 v[82:83], v[164:165], v[82:83], v[174:175] op_sel_hi:[0,1,1]
	v_pk_fma_f32 v[0:1], v[166:167], v[80:81], v[0:1] op_sel_hi:[0,1,1]
	v_pk_fma_f32 v[2:3], v[166:167], v[82:83], v[2:3] op_sel_hi:[0,1,1]
	ds_read_b128 v[164:167], v176 offset:5056
	s_waitcnt lgkmcnt(1)
	v_pk_mul_f32 v[172:173], v[168:169], v[152:153] op_sel:[1,0] op_sel_hi:[1,1]
	v_pk_mul_f32 v[174:175], v[168:169], v[154:155] op_sel:[1,0] op_sel_hi:[1,1]
	v_pk_fma_f32 v[80:81], v[168:169], v[80:81], v[172:173] op_sel_hi:[0,1,1]
	v_pk_fma_f32 v[82:83], v[168:169], v[82:83], v[174:175] op_sel_hi:[0,1,1]
	v_pk_fma_f32 v[4:5], v[170:171], v[80:81], v[4:5] op_sel_hi:[0,1,1]
	v_pk_fma_f32 v[6:7], v[170:171], v[82:83], v[6:7] op_sel_hi:[0,1,1]
	ds_read_b128 v[168:171], v176 offset:7104
	s_waitcnt lgkmcnt(1)
	v_pk_mul_f32 v[172:173], v[164:165], v[156:157] op_sel:[1,0] op_sel_hi:[1,1]
	v_pk_mul_f32 v[174:175], v[164:165], v[158:159] op_sel:[1,0] op_sel_hi:[1,1]
	v_pk_fma_f32 v[80:81], v[164:165], v[80:81], v[172:173] op_sel_hi:[0,1,1]
	v_pk_fma_f32 v[82:83], v[164:165], v[82:83], v[174:175] op_sel_hi:[0,1,1]
	v_pk_fma_f32 v[8:9], v[166:167], v[80:81], v[8:9] op_sel_hi:[0,1,1]
	v_pk_fma_f32 v[10:11], v[166:167], v[82:83], v[10:11] op_sel_hi:[0,1,1]
	ds_read_b128 v[164:167], v176 offset:1024
	s_waitcnt lgkmcnt(1)
; #define LAS __attribute__((address_space(3)))
; __device__ __forceinline__ void hgrn_sample_wave(LAS float* buf, const GAS float* Z, const GAS float* logits, int layer, int b, int h, int vh, const GAS float* Sin, GAS float* Sout, GAS bf16* OPB, int lane) {
;     ...
;     for (int dc = 0; dc < 16; ++dc) { float S[8];
; #pragma unroll
;         for (int dd = 0; dd < 8; ++dd) S[dd] = Sn[dd];
;         if (dc + 1 < 16) {
; #pragma unroll
;             for (int dd = 0; dd < 8; ++dd) Sn[dd] = __builtin_nontemporal_load(&Sin[((dc + 1) * 8 + dd) * 128 + vh * 64 + lane]); }
; #pragma unroll
;         for (int t = 0; t < 4; ++t)
; #pragma unroll
;             for (int dd = 0; dd < 8; ++dd) { const f32x4 op = *(const LAS f32x4*)(buf + (t * 128 + dc * 8 + dd) * 4); S[dd] = op.x * S[dd] + op.y * vt[t]; o[t] += op.z * S[dd]; }
; #pragma unroll
;         for (int dd = 0; dd < 8; ++dd) __builtin_nontemporal_store(S[dd], &Sout[(dc * 8 + dd) * 128 + vh * 64 + lane]); }
	v_pk_mul_f32 v[172:173], v[168:169], v[160:161] op_sel:[1,0] op_sel_hi:[1,1]
	v_pk_mul_f32 v[174:175], v[168:169], v[162:163] op_sel:[1,0] op_sel_hi:[1,1]
	v_pk_fma_f32 v[80:81], v[168:169], v[80:81], v[172:173] op_sel_hi:[0,1,1]
	v_pk_fma_f32 v[82:83], v[168:169], v[82:83], v[174:175] op_sel_hi:[0,1,1]
	v_pk_fma_f32 v[12:13], v[170:171], v[80:81], v[12:13] op_sel_hi:[0,1,1]
	v_pk_fma_f32 v[14:15], v[170:171], v[82:83], v[14:15] op_sel_hi:[0,1,1]
	ds_read_b128 v[168:171], v176 offset:3072
	global_store_dwordx4 v177, v[80:83], s[16:17] nt
	s_add_u32 s16, s16, 0x800
	s_addc_u32 s17, s17, 0
	s_waitcnt vmcnt(31)
	s_waitcnt lgkmcnt(1)
	v_pk_mul_f32 v[172:173], v[164:165], v[148:149] op_sel:[1,0] op_sel_hi:[1,1]
	v_pk_mul_f32 v[174:175], v[164:165], v[150:151] op_sel:[1,0] op_sel_hi:[1,1]
	v_pk_fma_f32 v[84:85], v[164:165], v[84:85], v[172:173] op_sel_hi:[0,1,1]
	v_pk_fma_f32 v[86:87], v[164:165], v[86:87], v[174:175] op_sel_hi:[0,1,1]
	v_pk_fma_f32 v[0:1], v[166:167], v[84:85], v[0:1] op_sel_hi:[0,1,1]
	v_pk_fma_f32 v[2:3], v[166:167], v[86:87], v[2:3] op_sel_hi:[0,1,1]
	ds_read_b128 v[164:167], v176 offset:5120
	s_waitcnt lgkmcnt(1)
	v_pk_mul_f32 v[172:173], v[168:169], v[152:153] op_sel:[1,0] op_sel_hi:[1,1]
	v_pk_mul_f32 v[174:175], v[168:169], v[154:155] op_sel:[1,0] op_sel_hi:[1,1]
	v_pk_fma_f32 v[84:85], v[168:169], v[84:85], v[172:173] op_sel_hi:[0,1,1]
	v_pk_fma_f32 v[86:87], v[168:169], v[86:87], v[174:175] op_sel_hi:[0,1,1]
	v_pk_fma_f32 v[4:5], v[170:171], v[84:85], v[4:5] op_sel_hi:[0,1,1]
	v_pk_fma_f32 v[6:7], v[170:171], v[86:87], v[6:7] op_sel_hi:[0,1,1]
	ds_read_b128 v[168:171], v176 offset:7168
	s_waitcnt lgkmcnt(1)
	v_pk_mul_f32 v[172:173], v[164:165], v[156:157] op_sel:[1,0] op_sel_hi:[1,1]
	v_pk_mul_f32 v[174:175], v[164:165], v[158:159] op_sel:[1,0] op_sel_hi:[1,1]
	v_pk_fma_f32 v[84:85], v[164:165], v[84:85], v[172:173] op_sel_hi:[0,1,1]
	v_pk_fma_f32 v[86:87], v[164:165], v[86:87], v[174:175] op_sel_hi:[0,1,1]
	v_pk_fma_f32 v[8:9], v[166:167], v[84:85], v[8:9] op_sel_hi:[0,1,1]
	v_pk_fma_f32 v[10:11], v[166:167], v[86:87], v[10:11] op_sel_hi:[0,1,1]
	ds_read_b128 v[164:167], v176 offset:1088
	s_waitcnt lgkmcnt(1)
	v_pk_mul_f32 v[172:173], v[168:169], v[160:161] op_sel:[1,0] op_sel_hi:[1,1]
	v_pk_mul_f32 v[174:175], v[168:169], v[162:163] op_sel:[1,0] op_sel_hi:[1,1]
	v_pk_fma_f32 v[84:85], v[168:169], v[84:85], v[172:173] op_sel_hi:[0,1,1]
	v_pk_fma_f32 v[86:87], v[168:169], v[86:87], v[174:175] op_sel_hi:[0,1,1]
	v_pk_fma_f32 v[12:13], v[170:171], v[84:85], v[12:13] op_sel_hi:[0,1,1]
	v_pk_fma_f32 v[14:15], v[170:171], v[86:87], v[14:15] op_sel_hi:[0,1,1]
	ds_read_b128 v[168:171], v176 offset:3136
	global_store_dwordx4 v177, v[84:87], s[16:17] nt
	s_add_u32 s16, s16, 0x800
	s_addc_u32 s17, s17, 0
	s_waitcnt vmcnt(31)
	s_waitcnt lgkmcnt(1)
	v_pk_mul_f32 v[172:173], v[164:165], v[148:149] op_sel:[1,0] op_sel_hi:[1,1]
	v_pk_mul_f32 v[174:175], v[164:165], v[150:151] op_sel:[1,0] op_sel_hi:[1,1]
	v_pk_fma_f32 v[88:89], v[164:165], v[88:89], v[172:173] op_sel_hi:[0,1,1]
	v_pk_fma_f32 v[90:91], v[164:165], v[90:91], v[174:175] op_sel_hi:[0,1,1]
	v_pk_fma_f32 v[0:1], v[166:167], v[88:89], v[0:1] op_sel_hi:[0,1,1]
	v_pk_fma_f32 v[2:3], v[166:167], v[90:91], v[2:3] op_sel_hi:[0,1,1]
	ds_read_b128 v[164:167], v176 offset:5184
	s_waitcnt lgkmcnt(1)
	v_pk_mul_f32 v[172:173], v[168:169], v[152:153] op_sel:[1,0] op_sel_hi:[1,1]
	v_pk_mul_f32 v[174:175], v[168:169], v[154:155] op_sel:[1,0] op_sel_hi:[1,1]
	v_pk_fma_f32 v[88:89], v[168:169], v[88:89], v[172:173] op_sel_hi:[0,1,1]
	v_pk_fma_f32 v[90:91], v[168:169], v[90:91], v[174:175] op_sel_hi:[0,1,1]
	v_pk_fma_f32 v[4:5], v[170:171], v[88:89], v[4:5] op_sel_hi:[0,1,1]
	v_pk_fma_f32 v[6:7], v[170:171], v[90:91], v[6:7] op_sel_hi:[0,1,1]
	ds_read_b128 v[168:171], v176 offset:7232
	s_waitcnt lgkmcnt(1)
	v_pk_mul_f32 v[172:173], v[164:165], v[156:157] op_sel:[1,0] op_sel_hi:[1,1]
	v_pk_mul_f32 v[174:175], v[164:165], v[158:159] op_sel:[1,0] op_sel_hi:[1,1]
	v_pk_fma_f32 v[88:89], v[164:165], v[88:89], v[172:173] op_sel_hi:[0,1,1]
	v_pk_fma_f32 v[90:91], v[164:165], v[90:91], v[174:175] op_sel_hi:[0,1,1]
	v_pk_fma_f32 v[8:9], v[166:167], v[88:89], v[8:9] op_sel_hi:[0,1,1]
	v_pk_fma_f32 v[10:11], v[166:167], v[90:91], v[10:11] op_sel_hi:[0,1,1]
	ds_read_b128 v[164:167], v176 offset:1152
	s_waitcnt lgkmcnt(1)
	v_pk_mul_f32 v[172:173], v[168:169], v[160:161] op_sel:[1,0] op_sel_hi:[1,1]
	v_pk_mul_f32 v[174:175], v[168:169], v[162:163] op_sel:[1,0] op_sel_hi:[1,1]
	v_pk_fma_f32 v[88:89], v[168:169], v[88:89], v[172:173] op_sel_hi:[0,1,1]
	v_pk_fma_f32 v[90:91], v[168:169], v[90:91], v[174:175] op_sel_hi:[0,1,1]
	v_pk_fma_f32 v[12:13], v[170:171], v[88:89], v[12:13] op_sel_hi:[0,1,1]
	v_pk_fma_f32 v[14:15], v[170:171], v[90:91], v[14:15] op_sel_hi:[0,1,1]
	ds_read_b128 v[168:171], v176 offset:3200
	global_store_dwordx4 v177, v[88:91], s[16:17] nt
	s_add_u32 s16, s16, 0x800
	s_addc_u32 s17, s17, 0
	s_waitcnt vmcnt(31)
	s_waitcnt lgkmcnt(1)
	v_pk_mul_f32 v[172:173], v[164:165], v[148:149] op_sel:[1,0] op_sel_hi:[1,1]
	v_pk_mul_f32 v[174:175], v[164:165], v[150:151] op_sel:[1,0] op_sel_hi:[1,1]
	v_pk_fma_f32 v[92:93], v[164:165], v[92:93], v[172:173] op_sel_hi:[0,1,1]
	v_pk_fma_f32 v[94:95], v[164:165], v[94:95], v[174:175] op_sel_hi:[0,1,1]
	v_pk_fma_f32 v[0:1], v[166:167], v[92:93], v[0:1] op_sel_hi:[0,1,1]
	v_pk_fma_f32 v[2:3], v[166:167], v[94:95], v[2:3] op_sel_hi:[0,1,1]
	ds_read_b128 v[164:167], v176 offset:5248
	s_waitcnt lgkmcnt(1)
; #define LAS __attribute__((address_space(3)))
; __device__ __forceinline__ void hgrn_sample_wave(LAS float* buf, const GAS float* Z, const GAS float* logits, int layer, int b, int h, int vh, const GAS float* Sin, GAS float* Sout, GAS bf16* OPB, int lane) {
;     ...
;     for (int dc = 0; dc < 16; ++dc) { float S[8];
; #pragma unroll
;         for (int dd = 0; dd < 8; ++dd) S[dd] = Sn[dd];
;         if (dc + 1 < 16) {
; #pragma unroll
;             for (int dd = 0; dd < 8; ++dd) Sn[dd] = __builtin_nontemporal_load(&Sin[((dc + 1) * 8 + dd) * 128 + vh * 64 + lane]); }
; #pragma unroll
;         for (int t = 0; t < 4; ++t)
; #pragma unroll
;             for (int dd = 0; dd < 8; ++dd) { const f32x4 op = *(const LAS f32x4*)(buf + (t * 128 + dc * 8 + dd) * 4); S[dd] = op.x * S[dd] + op.y * vt[t]; o[t] += op.z * S[dd]; }
; #pragma unroll
;         for (int dd = 0; dd < 8; ++dd) __builtin_nontemporal_store(S[dd], &Sout[(dc * 8 + dd) * 128 + vh * 64 + lane]); }
	v_pk_mul_f32 v[172:173], v[168:169], v[152:153] op_sel:[1,0] op_sel_hi:[1,1]
	v_pk_mul_f32 v[174:175], v[168:169], v[154:155] op_sel:[1,0] op_sel_hi:[1,1]
	v_pk_fma_f32 v[92:93], v[168:169], v[92:93], v[172:173] op_sel_hi:[0,1,1]
	v_pk_fma_f32 v[94:95], v[168:169], v[94:95], v[174:175] op_sel_hi:[0,1,1]
	v_pk_fma_f32 v[4:5], v[170:171], v[92:93], v[4:5] op_sel_hi:[0,1,1]
	v_pk_fma_f32 v[6:7], v[170:171], v[94:95], v[6:7] op_sel_hi:[0,1,1]
	ds_read_b128 v[168:171], v176 offset:7296
	s_waitcnt lgkmcnt(1)
	v_pk_mul_f32 v[172:173], v[164:165], v[156:157] op_sel:[1,0] op_sel_hi:[1,1]
	v_pk_mul_f32 v[174:175], v[164:165], v[158:159] op_sel:[1,0] op_sel_hi:[1,1]
	v_pk_fma_f32 v[92:93], v[164:165], v[92:93], v[172:173] op_sel_hi:[0,1,1]
	v_pk_fma_f32 v[94:95], v[164:165], v[94:95], v[174:175] op_sel_hi:[0,1,1]
	v_pk_fma_f32 v[8:9], v[166:167], v[92:93], v[8:9] op_sel_hi:[0,1,1]
	v_pk_fma_f32 v[10:11], v[166:167], v[94:95], v[10:11] op_sel_hi:[0,1,1]
	ds_read_b128 v[164:167], v176 offset:1216
	s_waitcnt lgkmcnt(1)
	v_pk_mul_f32 v[172:173], v[168:169], v[160:161] op_sel:[1,0] op_sel_hi:[1,1]
	v_pk_mul_f32 v[174:175], v[168:169], v[162:163] op_sel:[1,0] op_sel_hi:[1,1]
	v_pk_fma_f32 v[92:93], v[168:169], v[92:93], v[172:173] op_sel_hi:[0,1,1]
	v_pk_fma_f32 v[94:95], v[168:169], v[94:95], v[174:175] op_sel_hi:[0,1,1]
	v_pk_fma_f32 v[12:13], v[170:171], v[92:93], v[12:13] op_sel_hi:[0,1,1]
	v_pk_fma_f32 v[14:15], v[170:171], v[94:95], v[14:15] op_sel_hi:[0,1,1]
	ds_read_b128 v[168:171], v176 offset:3264
	global_store_dwordx4 v177, v[92:95], s[16:17] nt
	s_add_u32 s16, s16, 0x800
	s_addc_u32 s17, s17, 0
	s_waitcnt vmcnt(31)
	s_waitcnt lgkmcnt(1)
	v_pk_mul_f32 v[172:173], v[164:165], v[148:149] op_sel:[1,0] op_sel_hi:[1,1]
	v_pk_mul_f32 v[174:175], v[164:165], v[150:151] op_sel:[1,0] op_sel_hi:[1,1]
	v_pk_fma_f32 v[96:97], v[164:165], v[96:97], v[172:173] op_sel_hi:[0,1,1]
	v_pk_fma_f32 v[98:99], v[164:165], v[98:99], v[174:175] op_sel_hi:[0,1,1]
	v_pk_fma_f32 v[0:1], v[166:167], v[96:97], v[0:1] op_sel_hi:[0,1,1]
	v_pk_fma_f32 v[2:3], v[166:167], v[98:99], v[2:3] op_sel_hi:[0,1,1]
	ds_read_b128 v[164:167], v176 offset:5312
	s_waitcnt lgkmcnt(1)
	v_pk_mul_f32 v[172:173], v[168:169], v[152:153] op_sel:[1,0] op_sel_hi:[1,1]
	v_pk_mul_f32 v[174:175], v[168:169], v[154:155] op_sel:[1,0] op_sel_hi:[1,1]
	v_pk_fma_f32 v[96:97], v[168:169], v[96:97], v[172:173] op_sel_hi:[0,1,1]
	v_pk_fma_f32 v[98:99], v[168:169], v[98:99], v[174:175] op_sel_hi:[0,1,1]
	v_pk_fma_f32 v[4:5], v[170:171], v[96:97], v[4:5] op_sel_hi:[0,1,1]
	v_pk_fma_f32 v[6:7], v[170:171], v[98:99], v[6:7] op_sel_hi:[0,1,1]
	ds_read_b128 v[168:171], v176 offset:7360
	s_waitcnt lgkmcnt(1)
	v_pk_mul_f32 v[172:173], v[164:165], v[156:157] op_sel:[1,0] op_sel_hi:[1,1]
	v_pk_mul_f32 v[174:175], v[164:165], v[158:159] op_sel:[1,0] op_sel_hi:[1,1]
	v_pk_fma_f32 v[96:97], v[164:165], v[96:97], v[172:173] op_sel_hi:[0,1,1]
	v_pk_fma_f32 v[98:99], v[164:165], v[98:99], v[174:175] op_sel_hi:[0,1,1]
	v_pk_fma_f32 v[8:9], v[166:167], v[96:97], v[8:9] op_sel_hi:[0,1,1]
	v_pk_fma_f32 v[10:11], v[166:167], v[98:99], v[10:11] op_sel_hi:[0,1,1]
	ds_read_b128 v[164:167], v176 offset:1280
	s_waitcnt lgkmcnt(1)
	v_pk_mul_f32 v[172:173], v[168:169], v[160:161] op_sel:[1,0] op_sel_hi:[1,1]
	v_pk_mul_f32 v[174:175], v[168:169], v[162:163] op_sel:[1,0] op_sel_hi:[1,1]
	v_pk_fma_f32 v[96:97], v[168:169], v[96:97], v[172:173] op_sel_hi:[0,1,1]
	v_pk_fma_f32 v[98:99], v[168:169], v[98:99], v[174:175] op_sel_hi:[0,1,1]
	v_pk_fma_f32 v[12:13], v[170:171], v[96:97], v[12:13] op_sel_hi:[0,1,1]
	v_pk_fma_f32 v[14:15], v[170:171], v[98:99], v[14:15] op_sel_hi:[0,1,1]
	ds_read_b128 v[168:171], v176 offset:3328
	global_store_dwordx4 v177, v[96:99], s[16:17] nt
	s_add_u32 s16, s16, 0x800
	s_addc_u32 s17, s17, 0
	s_waitcnt vmcnt(31)
	s_waitcnt lgkmcnt(1)
	v_pk_mul_f32 v[172:173], v[164:165], v[148:149] op_sel:[1,0] op_sel_hi:[1,1]
	v_pk_mul_f32 v[174:175], v[164:165], v[150:151] op_sel:[1,0] op_sel_hi:[1,1]
	v_pk_fma_f32 v[100:101], v[164:165], v[100:101], v[172:173] op_sel_hi:[0,1,1]
	v_pk_fma_f32 v[102:103], v[164:165], v[102:103], v[174:175] op_sel_hi:[0,1,1]
	v_pk_fma_f32 v[0:1], v[166:167], v[100:101], v[0:1] op_sel_hi:[0,1,1]
	v_pk_fma_f32 v[2:3], v[166:167], v[102:103], v[2:3] op_sel_hi:[0,1,1]
	ds_read_b128 v[164:167], v176 offset:5376
	s_waitcnt lgkmcnt(1)
	v_pk_mul_f32 v[172:173], v[168:169], v[152:153] op_sel:[1,0] op_sel_hi:[1,1]
	v_pk_mul_f32 v[174:175], v[168:169], v[154:155] op_sel:[1,0] op_sel_hi:[1,1]
	v_pk_fma_f32 v[100:101], v[168:169], v[100:101], v[172:173] op_sel_hi:[0,1,1]
	v_pk_fma_f32 v[102:103], v[168:169], v[102:103], v[174:175] op_sel_hi:[0,1,1]
	v_pk_fma_f32 v[4:5], v[170:171], v[100:101], v[4:5] op_sel_hi:[0,1,1]
	v_pk_fma_f32 v[6:7], v[170:171], v[102:103], v[6:7] op_sel_hi:[0,1,1]
	ds_read_b128 v[168:171], v176 offset:7424
	s_waitcnt lgkmcnt(1)
	v_pk_mul_f32 v[172:173], v[164:165], v[156:157] op_sel:[1,0] op_sel_hi:[1,1]
	v_pk_mul_f32 v[174:175], v[164:165], v[158:159] op_sel:[1,0] op_sel_hi:[1,1]
	v_pk_fma_f32 v[100:101], v[164:165], v[100:101], v[172:173] op_sel_hi:[0,1,1]
	v_pk_fma_f32 v[102:103], v[164:165], v[102:103], v[174:175] op_sel_hi:[0,1,1]
	v_pk_fma_f32 v[8:9], v[166:167], v[100:101], v[8:9] op_sel_hi:[0,1,1]
	v_pk_fma_f32 v[10:11], v[166:167], v[102:103], v[10:11] op_sel_hi:[0,1,1]
	ds_read_b128 v[164:167], v176 offset:1344
	s_waitcnt lgkmcnt(1)
; #define LAS __attribute__((address_space(3)))
; __device__ __forceinline__ void hgrn_sample_wave(LAS float* buf, const GAS float* Z, const GAS float* logits, int layer, int b, int h, int vh, const GAS float* Sin, GAS float* Sout, GAS bf16* OPB, int lane) {
;     ...
;     for (int dc = 0; dc < 16; ++dc) { float S[8];
; #pragma unroll
;         for (int dd = 0; dd < 8; ++dd) S[dd] = Sn[dd];
;         if (dc + 1 < 16) {
; #pragma unroll
;             for (int dd = 0; dd < 8; ++dd) Sn[dd] = __builtin_nontemporal_load(&Sin[((dc + 1) * 8 + dd) * 128 + vh * 64 + lane]); }
; #pragma unroll
;         for (int t = 0; t < 4; ++t)
; #pragma unroll
;             for (int dd = 0; dd < 8; ++dd) { const f32x4 op = *(const LAS f32x4*)(buf + (t * 128 + dc * 8 + dd) * 4); S[dd] = op.x * S[dd] + op.y * vt[t]; o[t] += op.z * S[dd]; }
; #pragma unroll
;         for (int dd = 0; dd < 8; ++dd) __builtin_nontemporal_store(S[dd], &Sout[(dc * 8 + dd) * 128 + vh * 64 + lane]); }
	v_pk_mul_f32 v[172:173], v[168:169], v[160:161] op_sel:[1,0] op_sel_hi:[1,1]
	v_pk_mul_f32 v[174:175], v[168:169], v[162:163] op_sel:[1,0] op_sel_hi:[1,1]
	v_pk_fma_f32 v[100:101], v[168:169], v[100:101], v[172:173] op_sel_hi:[0,1,1]
	v_pk_fma_f32 v[102:103], v[168:169], v[102:103], v[174:175] op_sel_hi:[0,1,1]
	v_pk_fma_f32 v[12:13], v[170:171], v[100:101], v[12:13] op_sel_hi:[0,1,1]
	v_pk_fma_f32 v[14:15], v[170:171], v[102:103], v[14:15] op_sel_hi:[0,1,1]
	ds_read_b128 v[168:171], v176 offset:3392
	global_store_dwordx4 v177, v[100:103], s[16:17] nt
	s_add_u32 s16, s16, 0x800
	s_addc_u32 s17, s17, 0
	s_waitcnt vmcnt(31)
	s_waitcnt lgkmcnt(1)
	v_pk_mul_f32 v[172:173], v[164:165], v[148:149] op_sel:[1,0] op_sel_hi:[1,1]
	v_pk_mul_f32 v[174:175], v[164:165], v[150:151] op_sel:[1,0] op_sel_hi:[1,1]
	v_pk_fma_f32 v[104:105], v[164:165], v[104:105], v[172:173] op_sel_hi:[0,1,1]
	v_pk_fma_f32 v[106:107], v[164:165], v[106:107], v[174:175] op_sel_hi:[0,1,1]
	v_pk_fma_f32 v[0:1], v[166:167], v[104:105], v[0:1] op_sel_hi:[0,1,1]
	v_pk_fma_f32 v[2:3], v[166:167], v[106:107], v[2:3] op_sel_hi:[0,1,1]
	ds_read_b128 v[164:167], v176 offset:5440
	s_waitcnt lgkmcnt(1)
	v_pk_mul_f32 v[172:173], v[168:169], v[152:153] op_sel:[1,0] op_sel_hi:[1,1]
	v_pk_mul_f32 v[174:175], v[168:169], v[154:155] op_sel:[1,0] op_sel_hi:[1,1]
	v_pk_fma_f32 v[104:105], v[168:169], v[104:105], v[172:173] op_sel_hi:[0,1,1]
	v_pk_fma_f32 v[106:107], v[168:169], v[106:107], v[174:175] op_sel_hi:[0,1,1]
	v_pk_fma_f32 v[4:5], v[170:171], v[104:105], v[4:5] op_sel_hi:[0,1,1]
	v_pk_fma_f32 v[6:7], v[170:171], v[106:107], v[6:7] op_sel_hi:[0,1,1]
	ds_read_b128 v[168:171], v176 offset:7488
	s_waitcnt lgkmcnt(1)
	v_pk_mul_f32 v[172:173], v[164:165], v[156:157] op_sel:[1,0] op_sel_hi:[1,1]
	v_pk_mul_f32 v[174:175], v[164:165], v[158:159] op_sel:[1,0] op_sel_hi:[1,1]
	v_pk_fma_f32 v[104:105], v[164:165], v[104:105], v[172:173] op_sel_hi:[0,1,1]
	v_pk_fma_f32 v[106:107], v[164:165], v[106:107], v[174:175] op_sel_hi:[0,1,1]
	v_pk_fma_f32 v[8:9], v[166:167], v[104:105], v[8:9] op_sel_hi:[0,1,1]
	v_pk_fma_f32 v[10:11], v[166:167], v[106:107], v[10:11] op_sel_hi:[0,1,1]
	ds_read_b128 v[164:167], v176 offset:1408
	s_waitcnt lgkmcnt(1)
	v_pk_mul_f32 v[172:173], v[168:169], v[160:161] op_sel:[1,0] op_sel_hi:[1,1]
	v_pk_mul_f32 v[174:175], v[168:169], v[162:163] op_sel:[1,0] op_sel_hi:[1,1]
	v_pk_fma_f32 v[104:105], v[168:169], v[104:105], v[172:173] op_sel_hi:[0,1,1]
	v_pk_fma_f32 v[106:107], v[168:169], v[106:107], v[174:175] op_sel_hi:[0,1,1]
	v_pk_fma_f32 v[12:13], v[170:171], v[104:105], v[12:13] op_sel_hi:[0,1,1]
	v_pk_fma_f32 v[14:15], v[170:171], v[106:107], v[14:15] op_sel_hi:[0,1,1]
	ds_read_b128 v[168:171], v176 offset:3456
	global_store_dwordx4 v177, v[104:107], s[16:17] nt
	s_add_u32 s16, s16, 0x800
	s_addc_u32 s17, s17, 0
	s_waitcnt vmcnt(31)
	s_waitcnt lgkmcnt(1)
	v_pk_mul_f32 v[172:173], v[164:165], v[148:149] op_sel:[1,0] op_sel_hi:[1,1]
	v_pk_mul_f32 v[174:175], v[164:165], v[150:151] op_sel:[1,0] op_sel_hi:[1,1]
	v_pk_fma_f32 v[108:109], v[164:165], v[108:109], v[172:173] op_sel_hi:[0,1,1]
	v_pk_fma_f32 v[110:111], v[164:165], v[110:111], v[174:175] op_sel_hi:[0,1,1]
	v_pk_fma_f32 v[0:1], v[166:167], v[108:109], v[0:1] op_sel_hi:[0,1,1]
	v_pk_fma_f32 v[2:3], v[166:167], v[110:111], v[2:3] op_sel_hi:[0,1,1]
	ds_read_b128 v[164:167], v176 offset:5504
	s_waitcnt lgkmcnt(1)
	v_pk_mul_f32 v[172:173], v[168:169], v[152:153] op_sel:[1,0] op_sel_hi:[1,1]
	v_pk_mul_f32 v[174:175], v[168:169], v[154:155] op_sel:[1,0] op_sel_hi:[1,1]
	v_pk_fma_f32 v[108:109], v[168:169], v[108:109], v[172:173] op_sel_hi:[0,1,1]
	v_pk_fma_f32 v[110:111], v[168:169], v[110:111], v[174:175] op_sel_hi:[0,1,1]
	v_pk_fma_f32 v[4:5], v[170:171], v[108:109], v[4:5] op_sel_hi:[0,1,1]
	v_pk_fma_f32 v[6:7], v[170:171], v[110:111], v[6:7] op_sel_hi:[0,1,1]
	ds_read_b128 v[168:171], v176 offset:7552
	s_waitcnt lgkmcnt(1)
	v_pk_mul_f32 v[172:173], v[164:165], v[156:157] op_sel:[1,0] op_sel_hi:[1,1]
	v_pk_mul_f32 v[174:175], v[164:165], v[158:159] op_sel:[1,0] op_sel_hi:[1,1]
	v_pk_fma_f32 v[108:109], v[164:165], v[108:109], v[172:173] op_sel_hi:[0,1,1]
	v_pk_fma_f32 v[110:111], v[164:165], v[110:111], v[174:175] op_sel_hi:[0,1,1]
	v_pk_fma_f32 v[8:9], v[166:167], v[108:109], v[8:9] op_sel_hi:[0,1,1]
	v_pk_fma_f32 v[10:11], v[166:167], v[110:111], v[10:11] op_sel_hi:[0,1,1]
	ds_read_b128 v[164:167], v176 offset:1472
	s_waitcnt lgkmcnt(1)
	v_pk_mul_f32 v[172:173], v[168:169], v[160:161] op_sel:[1,0] op_sel_hi:[1,1]
	v_pk_mul_f32 v[174:175], v[168:169], v[162:163] op_sel:[1,0] op_sel_hi:[1,1]
	v_pk_fma_f32 v[108:109], v[168:169], v[108:109], v[172:173] op_sel_hi:[0,1,1]
	v_pk_fma_f32 v[110:111], v[168:169], v[110:111], v[174:175] op_sel_hi:[0,1,1]
	v_pk_fma_f32 v[12:13], v[170:171], v[108:109], v[12:13] op_sel_hi:[0,1,1]
	v_pk_fma_f32 v[14:15], v[170:171], v[110:111], v[14:15] op_sel_hi:[0,1,1]
	ds_read_b128 v[168:171], v176 offset:3520
	global_store_dwordx4 v177, v[108:111], s[16:17] nt
	s_add_u32 s16, s16, 0x800
	s_addc_u32 s17, s17, 0
	s_waitcnt vmcnt(31)
	s_waitcnt lgkmcnt(1)
	v_pk_mul_f32 v[172:173], v[164:165], v[148:149] op_sel:[1,0] op_sel_hi:[1,1]
	v_pk_mul_f32 v[174:175], v[164:165], v[150:151] op_sel:[1,0] op_sel_hi:[1,1]
	v_pk_fma_f32 v[112:113], v[164:165], v[112:113], v[172:173] op_sel_hi:[0,1,1]
	v_pk_fma_f32 v[114:115], v[164:165], v[114:115], v[174:175] op_sel_hi:[0,1,1]
	v_pk_fma_f32 v[0:1], v[166:167], v[112:113], v[0:1] op_sel_hi:[0,1,1]
	v_pk_fma_f32 v[2:3], v[166:167], v[114:115], v[2:3] op_sel_hi:[0,1,1]
	ds_read_b128 v[164:167], v176 offset:5568
	s_waitcnt lgkmcnt(1)
; #define LAS __attribute__((address_space(3)))
; __device__ __forceinline__ void hgrn_sample_wave(LAS float* buf, const GAS float* Z, const GAS float* logits, int layer, int b, int h, int vh, const GAS float* Sin, GAS float* Sout, GAS bf16* OPB, int lane) {
;     ...
;     for (int dc = 0; dc < 16; ++dc) { float S[8];
; #pragma unroll
;         for (int dd = 0; dd < 8; ++dd) S[dd] = Sn[dd];
;         if (dc + 1 < 16) {
; #pragma unroll
;             for (int dd = 0; dd < 8; ++dd) Sn[dd] = __builtin_nontemporal_load(&Sin[((dc + 1) * 8 + dd) * 128 + vh * 64 + lane]); }
; #pragma unroll
;         for (int t = 0; t < 4; ++t)
; #pragma unroll
;             for (int dd = 0; dd < 8; ++dd) { const f32x4 op = *(const LAS f32x4*)(buf + (t * 128 + dc * 8 + dd) * 4); S[dd] = op.x * S[dd] + op.y * vt[t]; o[t] += op.z * S[dd]; }
; #pragma unroll
;         for (int dd = 0; dd < 8; ++dd) __builtin_nontemporal_store(S[dd], &Sout[(dc * 8 + dd) * 128 + vh * 64 + lane]); }
	v_pk_mul_f32 v[172:173], v[168:169], v[152:153] op_sel:[1,0] op_sel_hi:[1,1]
	v_pk_mul_f32 v[174:175], v[168:169], v[154:155] op_sel:[1,0] op_sel_hi:[1,1]
	v_pk_fma_f32 v[112:113], v[168:169], v[112:113], v[172:173] op_sel_hi:[0,1,1]
	v_pk_fma_f32 v[114:115], v[168:169], v[114:115], v[174:175] op_sel_hi:[0,1,1]
	v_pk_fma_f32 v[4:5], v[170:171], v[112:113], v[4:5] op_sel_hi:[0,1,1]
	v_pk_fma_f32 v[6:7], v[170:171], v[114:115], v[6:7] op_sel_hi:[0,1,1]
	ds_read_b128 v[168:171], v176 offset:7616
	s_waitcnt lgkmcnt(1)
	v_pk_mul_f32 v[172:173], v[164:165], v[156:157] op_sel:[1,0] op_sel_hi:[1,1]
	v_pk_mul_f32 v[174:175], v[164:165], v[158:159] op_sel:[1,0] op_sel_hi:[1,1]
	v_pk_fma_f32 v[112:113], v[164:165], v[112:113], v[172:173] op_sel_hi:[0,1,1]
	v_pk_fma_f32 v[114:115], v[164:165], v[114:115], v[174:175] op_sel_hi:[0,1,1]
	v_pk_fma_f32 v[8:9], v[166:167], v[112:113], v[8:9] op_sel_hi:[0,1,1]
	v_pk_fma_f32 v[10:11], v[166:167], v[114:115], v[10:11] op_sel_hi:[0,1,1]
	ds_read_b128 v[164:167], v176 offset:1536
	s_waitcnt lgkmcnt(1)
	v_pk_mul_f32 v[172:173], v[168:169], v[160:161] op_sel:[1,0] op_sel_hi:[1,1]
	v_pk_mul_f32 v[174:175], v[168:169], v[162:163] op_sel:[1,0] op_sel_hi:[1,1]
	v_pk_fma_f32 v[112:113], v[168:169], v[112:113], v[172:173] op_sel_hi:[0,1,1]
	v_pk_fma_f32 v[114:115], v[168:169], v[114:115], v[174:175] op_sel_hi:[0,1,1]
	v_pk_fma_f32 v[12:13], v[170:171], v[112:113], v[12:13] op_sel_hi:[0,1,1]
	v_pk_fma_f32 v[14:15], v[170:171], v[114:115], v[14:15] op_sel_hi:[0,1,1]
	ds_read_b128 v[168:171], v176 offset:3584
	global_store_dwordx4 v177, v[112:115], s[16:17] nt
	s_add_u32 s16, s16, 0x800
	s_addc_u32 s17, s17, 0
	s_waitcnt vmcnt(31)
	s_waitcnt lgkmcnt(1)
	v_pk_mul_f32 v[172:173], v[164:165], v[148:149] op_sel:[1,0] op_sel_hi:[1,1]
	v_pk_mul_f32 v[174:175], v[164:165], v[150:151] op_sel:[1,0] op_sel_hi:[1,1]
	v_pk_fma_f32 v[116:117], v[164:165], v[116:117], v[172:173] op_sel_hi:[0,1,1]
	v_pk_fma_f32 v[118:119], v[164:165], v[118:119], v[174:175] op_sel_hi:[0,1,1]
	v_pk_fma_f32 v[0:1], v[166:167], v[116:117], v[0:1] op_sel_hi:[0,1,1]
	v_pk_fma_f32 v[2:3], v[166:167], v[118:119], v[2:3] op_sel_hi:[0,1,1]
	ds_read_b128 v[164:167], v176 offset:5632
	s_waitcnt lgkmcnt(1)
	v_pk_mul_f32 v[172:173], v[168:169], v[152:153] op_sel:[1,0] op_sel_hi:[1,1]
	v_pk_mul_f32 v[174:175], v[168:169], v[154:155] op_sel:[1,0] op_sel_hi:[1,1]
	v_pk_fma_f32 v[116:117], v[168:169], v[116:117], v[172:173] op_sel_hi:[0,1,1]
	v_pk_fma_f32 v[118:119], v[168:169], v[118:119], v[174:175] op_sel_hi:[0,1,1]
	v_pk_fma_f32 v[4:5], v[170:171], v[116:117], v[4:5] op_sel_hi:[0,1,1]
	v_pk_fma_f32 v[6:7], v[170:171], v[118:119], v[6:7] op_sel_hi:[0,1,1]
	ds_read_b128 v[168:171], v176 offset:7680
	s_waitcnt lgkmcnt(1)
	v_pk_mul_f32 v[172:173], v[164:165], v[156:157] op_sel:[1,0] op_sel_hi:[1,1]
	v_pk_mul_f32 v[174:175], v[164:165], v[158:159] op_sel:[1,0] op_sel_hi:[1,1]
	v_pk_fma_f32 v[116:117], v[164:165], v[116:117], v[172:173] op_sel_hi:[0,1,1]
	v_pk_fma_f32 v[118:119], v[164:165], v[118:119], v[174:175] op_sel_hi:[0,1,1]
	v_pk_fma_f32 v[8:9], v[166:167], v[116:117], v[8:9] op_sel_hi:[0,1,1]
	v_pk_fma_f32 v[10:11], v[166:167], v[118:119], v[10:11] op_sel_hi:[0,1,1]
	ds_read_b128 v[164:167], v176 offset:1600
	s_waitcnt lgkmcnt(1)
	v_pk_mul_f32 v[172:173], v[168:169], v[160:161] op_sel:[1,0] op_sel_hi:[1,1]
	v_pk_mul_f32 v[174:175], v[168:169], v[162:163] op_sel:[1,0] op_sel_hi:[1,1]
	v_pk_fma_f32 v[116:117], v[168:169], v[116:117], v[172:173] op_sel_hi:[0,1,1]
	v_pk_fma_f32 v[118:119], v[168:169], v[118:119], v[174:175] op_sel_hi:[0,1,1]
	v_pk_fma_f32 v[12:13], v[170:171], v[116:117], v[12:13] op_sel_hi:[0,1,1]
	v_pk_fma_f32 v[14:15], v[170:171], v[118:119], v[14:15] op_sel_hi:[0,1,1]
	ds_read_b128 v[168:171], v176 offset:3648
	global_store_dwordx4 v177, v[116:119], s[16:17] nt
	s_add_u32 s16, s16, 0x800
	s_addc_u32 s17, s17, 0
	s_waitcnt vmcnt(31)
	s_waitcnt lgkmcnt(1)
	v_pk_mul_f32 v[172:173], v[164:165], v[148:149] op_sel:[1,0] op_sel_hi:[1,1]
	v_pk_mul_f32 v[174:175], v[164:165], v[150:151] op_sel:[1,0] op_sel_hi:[1,1]
	v_pk_fma_f32 v[120:121], v[164:165], v[120:121], v[172:173] op_sel_hi:[0,1,1]
	v_pk_fma_f32 v[122:123], v[164:165], v[122:123], v[174:175] op_sel_hi:[0,1,1]
	v_pk_fma_f32 v[0:1], v[166:167], v[120:121], v[0:1] op_sel_hi:[0,1,1]
	v_pk_fma_f32 v[2:3], v[166:167], v[122:123], v[2:3] op_sel_hi:[0,1,1]
	ds_read_b128 v[164:167], v176 offset:5696
	s_waitcnt lgkmcnt(1)
	v_pk_mul_f32 v[172:173], v[168:169], v[152:153] op_sel:[1,0] op_sel_hi:[1,1]
	v_pk_mul_f32 v[174:175], v[168:169], v[154:155] op_sel:[1,0] op_sel_hi:[1,1]
	v_pk_fma_f32 v[120:121], v[168:169], v[120:121], v[172:173] op_sel_hi:[0,1,1]
	v_pk_fma_f32 v[122:123], v[168:169], v[122:123], v[174:175] op_sel_hi:[0,1,1]
	v_pk_fma_f32 v[4:5], v[170:171], v[120:121], v[4:5] op_sel_hi:[0,1,1]
	v_pk_fma_f32 v[6:7], v[170:171], v[122:123], v[6:7] op_sel_hi:[0,1,1]
	ds_read_b128 v[168:171], v176 offset:7744
	s_waitcnt lgkmcnt(1)
	v_pk_mul_f32 v[172:173], v[164:165], v[156:157] op_sel:[1,0] op_sel_hi:[1,1]
	v_pk_mul_f32 v[174:175], v[164:165], v[158:159] op_sel:[1,0] op_sel_hi:[1,1]
	v_pk_fma_f32 v[120:121], v[164:165], v[120:121], v[172:173] op_sel_hi:[0,1,1]
	v_pk_fma_f32 v[122:123], v[164:165], v[122:123], v[174:175] op_sel_hi:[0,1,1]
	v_pk_fma_f32 v[8:9], v[166:167], v[120:121], v[8:9] op_sel_hi:[0,1,1]
	v_pk_fma_f32 v[10:11], v[166:167], v[122:123], v[10:11] op_sel_hi:[0,1,1]
	ds_read_b128 v[164:167], v176 offset:1664
	s_waitcnt lgkmcnt(1)
; #define LAS __attribute__((address_space(3)))
; __device__ __forceinline__ void hgrn_sample_wave(LAS float* buf, const GAS float* Z, const GAS float* logits, int layer, int b, int h, int vh, const GAS float* Sin, GAS float* Sout, GAS bf16* OPB, int lane) {
;     ...
;     for (int dc = 0; dc < 16; ++dc) { float S[8];
; #pragma unroll
;         for (int dd = 0; dd < 8; ++dd) S[dd] = Sn[dd];
;         if (dc + 1 < 16) {
; #pragma unroll
;             for (int dd = 0; dd < 8; ++dd) Sn[dd] = __builtin_nontemporal_load(&Sin[((dc + 1) * 8 + dd) * 128 + vh * 64 + lane]); }
; #pragma unroll
;         for (int t = 0; t < 4; ++t)
; #pragma unroll
;             for (int dd = 0; dd < 8; ++dd) { const f32x4 op = *(const LAS f32x4*)(buf + (t * 128 + dc * 8 + dd) * 4); S[dd] = op.x * S[dd] + op.y * vt[t]; o[t] += op.z * S[dd]; }
; #pragma unroll
;         for (int dd = 0; dd < 8; ++dd) __builtin_nontemporal_store(S[dd], &Sout[(dc * 8 + dd) * 128 + vh * 64 + lane]); }
	v_pk_mul_f32 v[172:173], v[168:169], v[160:161] op_sel:[1,0] op_sel_hi:[1,1]
	v_pk_mul_f32 v[174:175], v[168:169], v[162:163] op_sel:[1,0] op_sel_hi:[1,1]
	v_pk_fma_f32 v[120:121], v[168:169], v[120:121], v[172:173] op_sel_hi:[0,1,1]
	v_pk_fma_f32 v[122:123], v[168:169], v[122:123], v[174:175] op_sel_hi:[0,1,1]
	v_pk_fma_f32 v[12:13], v[170:171], v[120:121], v[12:13] op_sel_hi:[0,1,1]
	v_pk_fma_f32 v[14:15], v[170:171], v[122:123], v[14:15] op_sel_hi:[0,1,1]
	ds_read_b128 v[168:171], v176 offset:3712
	global_store_dwordx4 v177, v[120:123], s[16:17] nt
	s_add_u32 s16, s16, 0x800
	s_addc_u32 s17, s17, 0
	s_waitcnt vmcnt(31)
	s_waitcnt lgkmcnt(1)
	v_pk_mul_f32 v[172:173], v[164:165], v[148:149] op_sel:[1,0] op_sel_hi:[1,1]
	v_pk_mul_f32 v[174:175], v[164:165], v[150:151] op_sel:[1,0] op_sel_hi:[1,1]
	v_pk_fma_f32 v[124:125], v[164:165], v[124:125], v[172:173] op_sel_hi:[0,1,1]
	v_pk_fma_f32 v[126:127], v[164:165], v[126:127], v[174:175] op_sel_hi:[0,1,1]
	v_pk_fma_f32 v[0:1], v[166:167], v[124:125], v[0:1] op_sel_hi:[0,1,1]
	v_pk_fma_f32 v[2:3], v[166:167], v[126:127], v[2:3] op_sel_hi:[0,1,1]
	ds_read_b128 v[164:167], v176 offset:5760
	s_waitcnt lgkmcnt(1)
	v_pk_mul_f32 v[172:173], v[168:169], v[152:153] op_sel:[1,0] op_sel_hi:[1,1]
	v_pk_mul_f32 v[174:175], v[168:169], v[154:155] op_sel:[1,0] op_sel_hi:[1,1]
	v_pk_fma_f32 v[124:125], v[168:169], v[124:125], v[172:173] op_sel_hi:[0,1,1]
	v_pk_fma_f32 v[126:127], v[168:169], v[126:127], v[174:175] op_sel_hi:[0,1,1]
	v_pk_fma_f32 v[4:5], v[170:171], v[124:125], v[4:5] op_sel_hi:[0,1,1]
	v_pk_fma_f32 v[6:7], v[170:171], v[126:127], v[6:7] op_sel_hi:[0,1,1]
	ds_read_b128 v[168:171], v176 offset:7808
	s_waitcnt lgkmcnt(1)
	v_pk_mul_f32 v[172:173], v[164:165], v[156:157] op_sel:[1,0] op_sel_hi:[1,1]
	v_pk_mul_f32 v[174:175], v[164:165], v[158:159] op_sel:[1,0] op_sel_hi:[1,1]
	v_pk_fma_f32 v[124:125], v[164:165], v[124:125], v[172:173] op_sel_hi:[0,1,1]
	v_pk_fma_f32 v[126:127], v[164:165], v[126:127], v[174:175] op_sel_hi:[0,1,1]
	v_pk_fma_f32 v[8:9], v[166:167], v[124:125], v[8:9] op_sel_hi:[0,1,1]
	v_pk_fma_f32 v[10:11], v[166:167], v[126:127], v[10:11] op_sel_hi:[0,1,1]
	ds_read_b128 v[164:167], v176 offset:1728
	s_waitcnt lgkmcnt(1)
	v_pk_mul_f32 v[172:173], v[168:169], v[160:161] op_sel:[1,0] op_sel_hi:[1,1]
	v_pk_mul_f32 v[174:175], v[168:169], v[162:163] op_sel:[1,0] op_sel_hi:[1,1]
	v_pk_fma_f32 v[124:125], v[168:169], v[124:125], v[172:173] op_sel_hi:[0,1,1]
	v_pk_fma_f32 v[126:127], v[168:169], v[126:127], v[174:175] op_sel_hi:[0,1,1]
	v_pk_fma_f32 v[12:13], v[170:171], v[124:125], v[12:13] op_sel_hi:[0,1,1]
	v_pk_fma_f32 v[14:15], v[170:171], v[126:127], v[14:15] op_sel_hi:[0,1,1]
	ds_read_b128 v[168:171], v176 offset:3776
	global_store_dwordx4 v177, v[124:127], s[16:17] nt
	s_add_u32 s16, s16, 0x800
	s_addc_u32 s17, s17, 0
	s_waitcnt vmcnt(31)
	s_waitcnt lgkmcnt(1)
	v_pk_mul_f32 v[172:173], v[164:165], v[148:149] op_sel:[1,0] op_sel_hi:[1,1]
	v_pk_mul_f32 v[174:175], v[164:165], v[150:151] op_sel:[1,0] op_sel_hi:[1,1]
	v_pk_fma_f32 v[128:129], v[164:165], v[128:129], v[172:173] op_sel_hi:[0,1,1]
	v_pk_fma_f32 v[130:131], v[164:165], v[130:131], v[174:175] op_sel_hi:[0,1,1]
	v_pk_fma_f32 v[0:1], v[166:167], v[128:129], v[0:1] op_sel_hi:[0,1,1]
	v_pk_fma_f32 v[2:3], v[166:167], v[130:131], v[2:3] op_sel_hi:[0,1,1]
	ds_read_b128 v[164:167], v176 offset:5824
	s_waitcnt lgkmcnt(1)
	v_pk_mul_f32 v[172:173], v[168:169], v[152:153] op_sel:[1,0] op_sel_hi:[1,1]
	v_pk_mul_f32 v[174:175], v[168:169], v[154:155] op_sel:[1,0] op_sel_hi:[1,1]
	v_pk_fma_f32 v[128:129], v[168:169], v[128:129], v[172:173] op_sel_hi:[0,1,1]
	v_pk_fma_f32 v[130:131], v[168:169], v[130:131], v[174:175] op_sel_hi:[0,1,1]
	v_pk_fma_f32 v[4:5], v[170:171], v[128:129], v[4:5] op_sel_hi:[0,1,1]
	v_pk_fma_f32 v[6:7], v[170:171], v[130:131], v[6:7] op_sel_hi:[0,1,1]
	ds_read_b128 v[168:171], v176 offset:7872
	s_waitcnt lgkmcnt(1)
	v_pk_mul_f32 v[172:173], v[164:165], v[156:157] op_sel:[1,0] op_sel_hi:[1,1]
	v_pk_mul_f32 v[174:175], v[164:165], v[158:159] op_sel:[1,0] op_sel_hi:[1,1]
	v_pk_fma_f32 v[128:129], v[164:165], v[128:129], v[172:173] op_sel_hi:[0,1,1]
	v_pk_fma_f32 v[130:131], v[164:165], v[130:131], v[174:175] op_sel_hi:[0,1,1]
	v_pk_fma_f32 v[8:9], v[166:167], v[128:129], v[8:9] op_sel_hi:[0,1,1]
	v_pk_fma_f32 v[10:11], v[166:167], v[130:131], v[10:11] op_sel_hi:[0,1,1]
	ds_read_b128 v[164:167], v176 offset:1792
	s_waitcnt lgkmcnt(1)
	v_pk_mul_f32 v[172:173], v[168:169], v[160:161] op_sel:[1,0] op_sel_hi:[1,1]
	v_pk_mul_f32 v[174:175], v[168:169], v[162:163] op_sel:[1,0] op_sel_hi:[1,1]
	v_pk_fma_f32 v[128:129], v[168:169], v[128:129], v[172:173] op_sel_hi:[0,1,1]
	v_pk_fma_f32 v[130:131], v[168:169], v[130:131], v[174:175] op_sel_hi:[0,1,1]
	v_pk_fma_f32 v[12:13], v[170:171], v[128:129], v[12:13] op_sel_hi:[0,1,1]
	v_pk_fma_f32 v[14:15], v[170:171], v[130:131], v[14:15] op_sel_hi:[0,1,1]
	ds_read_b128 v[168:171], v176 offset:3840
	global_store_dwordx4 v177, v[128:131], s[16:17] nt
	s_add_u32 s16, s16, 0x800
	s_addc_u32 s17, s17, 0
	s_waitcnt vmcnt(31)
	s_waitcnt lgkmcnt(1)
	v_pk_mul_f32 v[172:173], v[164:165], v[148:149] op_sel:[1,0] op_sel_hi:[1,1]
	v_pk_mul_f32 v[174:175], v[164:165], v[150:151] op_sel:[1,0] op_sel_hi:[1,1]
	v_pk_fma_f32 v[132:133], v[164:165], v[132:133], v[172:173] op_sel_hi:[0,1,1]
	v_pk_fma_f32 v[134:135], v[164:165], v[134:135], v[174:175] op_sel_hi:[0,1,1]
	v_pk_fma_f32 v[0:1], v[166:167], v[132:133], v[0:1] op_sel_hi:[0,1,1]
	v_pk_fma_f32 v[2:3], v[166:167], v[134:135], v[2:3] op_sel_hi:[0,1,1]
	ds_read_b128 v[164:167], v176 offset:5888
	s_waitcnt lgkmcnt(1)
; #define LAS __attribute__((address_space(3)))
; __device__ __forceinline__ void hgrn_sample_wave(LAS float* buf, const GAS float* Z, const GAS float* logits, int layer, int b, int h, int vh, const GAS float* Sin, GAS float* Sout, GAS bf16* OPB, int lane) {
;     ...
;     for (int dc = 0; dc < 16; ++dc) { float S[8];
; #pragma unroll
;         for (int dd = 0; dd < 8; ++dd) S[dd] = Sn[dd];
;         if (dc + 1 < 16) {
; #pragma unroll
;             for (int dd = 0; dd < 8; ++dd) Sn[dd] = __builtin_nontemporal_load(&Sin[((dc + 1) * 8 + dd) * 128 + vh * 64 + lane]); }
; #pragma unroll
;         for (int t = 0; t < 4; ++t)
; #pragma unroll
;             for (int dd = 0; dd < 8; ++dd) { const f32x4 op = *(const LAS f32x4*)(buf + (t * 128 + dc * 8 + dd) * 4); S[dd] = op.x * S[dd] + op.y * vt[t]; o[t] += op.z * S[dd]; }
; #pragma unroll
;         for (int dd = 0; dd < 8; ++dd) __builtin_nontemporal_store(S[dd], &Sout[(dc * 8 + dd) * 128 + vh * 64 + lane]); }
	v_pk_mul_f32 v[172:173], v[168:169], v[152:153] op_sel:[1,0] op_sel_hi:[1,1]
	v_pk_mul_f32 v[174:175], v[168:169], v[154:155] op_sel:[1,0] op_sel_hi:[1,1]
	v_pk_fma_f32 v[132:133], v[168:169], v[132:133], v[172:173] op_sel_hi:[0,1,1]
	v_pk_fma_f32 v[134:135], v[168:169], v[134:135], v[174:175] op_sel_hi:[0,1,1]
	v_pk_fma_f32 v[4:5], v[170:171], v[132:133], v[4:5] op_sel_hi:[0,1,1]
	v_pk_fma_f32 v[6:7], v[170:171], v[134:135], v[6:7] op_sel_hi:[0,1,1]
	ds_read_b128 v[168:171], v176 offset:7936
	s_waitcnt lgkmcnt(1)
	v_pk_mul_f32 v[172:173], v[164:165], v[156:157] op_sel:[1,0] op_sel_hi:[1,1]
	v_pk_mul_f32 v[174:175], v[164:165], v[158:159] op_sel:[1,0] op_sel_hi:[1,1]
	v_pk_fma_f32 v[132:133], v[164:165], v[132:133], v[172:173] op_sel_hi:[0,1,1]
	v_pk_fma_f32 v[134:135], v[164:165], v[134:135], v[174:175] op_sel_hi:[0,1,1]
	v_pk_fma_f32 v[8:9], v[166:167], v[132:133], v[8:9] op_sel_hi:[0,1,1]
	v_pk_fma_f32 v[10:11], v[166:167], v[134:135], v[10:11] op_sel_hi:[0,1,1]
	ds_read_b128 v[164:167], v176 offset:1856
	s_waitcnt lgkmcnt(1)
	v_pk_mul_f32 v[172:173], v[168:169], v[160:161] op_sel:[1,0] op_sel_hi:[1,1]
	v_pk_mul_f32 v[174:175], v[168:169], v[162:163] op_sel:[1,0] op_sel_hi:[1,1]
	v_pk_fma_f32 v[132:133], v[168:169], v[132:133], v[172:173] op_sel_hi:[0,1,1]
	v_pk_fma_f32 v[134:135], v[168:169], v[134:135], v[174:175] op_sel_hi:[0,1,1]
	v_pk_fma_f32 v[12:13], v[170:171], v[132:133], v[12:13] op_sel_hi:[0,1,1]
	v_pk_fma_f32 v[14:15], v[170:171], v[134:135], v[14:15] op_sel_hi:[0,1,1]
	ds_read_b128 v[168:171], v176 offset:3904
	global_store_dwordx4 v177, v[132:135], s[16:17] nt
	s_add_u32 s16, s16, 0x800
	s_addc_u32 s17, s17, 0
	s_waitcnt vmcnt(31)
	s_waitcnt lgkmcnt(1)
	v_pk_mul_f32 v[172:173], v[164:165], v[148:149] op_sel:[1,0] op_sel_hi:[1,1]
	v_pk_mul_f32 v[174:175], v[164:165], v[150:151] op_sel:[1,0] op_sel_hi:[1,1]
	v_pk_fma_f32 v[136:137], v[164:165], v[136:137], v[172:173] op_sel_hi:[0,1,1]
	v_pk_fma_f32 v[138:139], v[164:165], v[138:139], v[174:175] op_sel_hi:[0,1,1]
	v_pk_fma_f32 v[0:1], v[166:167], v[136:137], v[0:1] op_sel_hi:[0,1,1]
	v_pk_fma_f32 v[2:3], v[166:167], v[138:139], v[2:3] op_sel_hi:[0,1,1]
	ds_read_b128 v[164:167], v176 offset:5952
	s_waitcnt lgkmcnt(1)
	v_pk_mul_f32 v[172:173], v[168:169], v[152:153] op_sel:[1,0] op_sel_hi:[1,1]
	v_pk_mul_f32 v[174:175], v[168:169], v[154:155] op_sel:[1,0] op_sel_hi:[1,1]
	v_pk_fma_f32 v[136:137], v[168:169], v[136:137], v[172:173] op_sel_hi:[0,1,1]
	v_pk_fma_f32 v[138:139], v[168:169], v[138:139], v[174:175] op_sel_hi:[0,1,1]
	v_pk_fma_f32 v[4:5], v[170:171], v[136:137], v[4:5] op_sel_hi:[0,1,1]
	v_pk_fma_f32 v[6:7], v[170:171], v[138:139], v[6:7] op_sel_hi:[0,1,1]
	ds_read_b128 v[168:171], v176 offset:8000
	s_waitcnt lgkmcnt(1)
	v_pk_mul_f32 v[172:173], v[164:165], v[156:157] op_sel:[1,0] op_sel_hi:[1,1]
	v_pk_mul_f32 v[174:175], v[164:165], v[158:159] op_sel:[1,0] op_sel_hi:[1,1]
	v_pk_fma_f32 v[136:137], v[164:165], v[136:137], v[172:173] op_sel_hi:[0,1,1]
	v_pk_fma_f32 v[138:139], v[164:165], v[138:139], v[174:175] op_sel_hi:[0,1,1]
	v_pk_fma_f32 v[8:9], v[166:167], v[136:137], v[8:9] op_sel_hi:[0,1,1]
	v_pk_fma_f32 v[10:11], v[166:167], v[138:139], v[10:11] op_sel_hi:[0,1,1]
	ds_read_b128 v[164:167], v176 offset:1920
	s_waitcnt lgkmcnt(1)
	v_pk_mul_f32 v[172:173], v[168:169], v[160:161] op_sel:[1,0] op_sel_hi:[1,1]
	v_pk_mul_f32 v[174:175], v[168:169], v[162:163] op_sel:[1,0] op_sel_hi:[1,1]
	v_pk_fma_f32 v[136:137], v[168:169], v[136:137], v[172:173] op_sel_hi:[0,1,1]
	v_pk_fma_f32 v[138:139], v[168:169], v[138:139], v[174:175] op_sel_hi:[0,1,1]
	v_pk_fma_f32 v[12:13], v[170:171], v[136:137], v[12:13] op_sel_hi:[0,1,1]
	v_pk_fma_f32 v[14:15], v[170:171], v[138:139], v[14:15] op_sel_hi:[0,1,1]
	ds_read_b128 v[168:171], v176 offset:3968
	global_store_dwordx4 v177, v[136:139], s[16:17] nt
	s_add_u32 s16, s16, 0x800
	s_addc_u32 s17, s17, 0
	s_waitcnt vmcnt(31)
	s_waitcnt lgkmcnt(1)
	v_pk_mul_f32 v[172:173], v[164:165], v[148:149] op_sel:[1,0] op_sel_hi:[1,1]
	v_pk_mul_f32 v[174:175], v[164:165], v[150:151] op_sel:[1,0] op_sel_hi:[1,1]
	v_pk_fma_f32 v[140:141], v[164:165], v[140:141], v[172:173] op_sel_hi:[0,1,1]
	v_pk_fma_f32 v[142:143], v[164:165], v[142:143], v[174:175] op_sel_hi:[0,1,1]
	v_pk_fma_f32 v[0:1], v[166:167], v[140:141], v[0:1] op_sel_hi:[0,1,1]
	v_pk_fma_f32 v[2:3], v[166:167], v[142:143], v[2:3] op_sel_hi:[0,1,1]
	ds_read_b128 v[164:167], v176 offset:6016
	s_waitcnt lgkmcnt(1)
	v_pk_mul_f32 v[172:173], v[168:169], v[152:153] op_sel:[1,0] op_sel_hi:[1,1]
	v_pk_mul_f32 v[174:175], v[168:169], v[154:155] op_sel:[1,0] op_sel_hi:[1,1]
	v_pk_fma_f32 v[140:141], v[168:169], v[140:141], v[172:173] op_sel_hi:[0,1,1]
	v_pk_fma_f32 v[142:143], v[168:169], v[142:143], v[174:175] op_sel_hi:[0,1,1]
	v_pk_fma_f32 v[4:5], v[170:171], v[140:141], v[4:5] op_sel_hi:[0,1,1]
	v_pk_fma_f32 v[6:7], v[170:171], v[142:143], v[6:7] op_sel_hi:[0,1,1]
	ds_read_b128 v[168:171], v176 offset:8064
	s_waitcnt lgkmcnt(1)
; #define LAS __attribute__((address_space(3)))
; __device__ __forceinline__ unsigned pk2(float lo, float hi) { return pg8::cvt_pk_bf16(lo, hi); }
; __device__ __forceinline__ bf16 bf1(float v) { return (bf16)(pg8::cvt_pk_bf16(v, 0.f) & 0xffffu); }
; __device__ __forceinline__ void hgrn_sample_wave(LAS float* buf, const GAS float* Z, const GAS float* logits, int layer, int b, int h, int vh, const GAS float* Sin, GAS float* Sout, GAS bf16* OPB, int lane) {
;     ...
;     for (int dc = 0; dc < 16; ++dc) { float S[8];
; #pragma unroll
;         for (int dd = 0; dd < 8; ++dd) S[dd] = Sn[dd];
;         if (dc + 1 < 16) {
; #pragma unroll
;             for (int dd = 0; dd < 8; ++dd) Sn[dd] = __builtin_nontemporal_load(&Sin[((dc + 1) * 8 + dd) * 128 + vh * 64 + lane]); }
; #pragma unroll
;         for (int t = 0; t < 4; ++t)
; #pragma unroll
;             for (int dd = 0; dd < 8; ++dd) { const f32x4 op = *(const LAS f32x4*)(buf + (t * 128 + dc * 8 + dd) * 4); S[dd] = op.x * S[dd] + op.y * vt[t]; o[t] += op.z * S[dd]; }
; #pragma unroll
;         for (int dd = 0; dd < 8; ++dd) __builtin_nontemporal_store(S[dd], &Sout[(dc * 8 + dd) * 128 + vh * 64 + lane]); }
; #pragma unroll
;     for (int t = 0; t < 4; ++t) { const size_t oi = (size_t)(mbase + t) * 512 + h * 128 + vh * 64 + lane; const unsigned hi = pk2(o[t], 0.f) & 0xffffu; const float hf = __builtin_bit_cast(float, hi << 16);
;         OPB[oi] = (bf16)hi; OPB[SZ + oi] = bf1(o[t] - hf); }
	v_pk_mul_f32 v[172:173], v[164:165], v[156:157] op_sel:[1,0] op_sel_hi:[1,1]
	v_pk_mul_f32 v[174:175], v[164:165], v[158:159] op_sel:[1,0] op_sel_hi:[1,1]
	v_pk_fma_f32 v[140:141], v[164:165], v[140:141], v[172:173] op_sel_hi:[0,1,1]
	v_pk_fma_f32 v[142:143], v[164:165], v[142:143], v[174:175] op_sel_hi:[0,1,1]
	v_pk_fma_f32 v[8:9], v[166:167], v[140:141], v[8:9] op_sel_hi:[0,1,1]
	v_pk_fma_f32 v[10:11], v[166:167], v[142:143], v[10:11] op_sel_hi:[0,1,1]
	ds_read_b128 v[164:167], v176 offset:1984
	s_waitcnt lgkmcnt(1)
	v_pk_mul_f32 v[172:173], v[168:169], v[160:161] op_sel:[1,0] op_sel_hi:[1,1]
	v_pk_mul_f32 v[174:175], v[168:169], v[162:163] op_sel:[1,0] op_sel_hi:[1,1]
	v_pk_fma_f32 v[140:141], v[168:169], v[140:141], v[172:173] op_sel_hi:[0,1,1]
	v_pk_fma_f32 v[142:143], v[168:169], v[142:143], v[174:175] op_sel_hi:[0,1,1]
	v_pk_fma_f32 v[12:13], v[170:171], v[140:141], v[12:13] op_sel_hi:[0,1,1]
	v_pk_fma_f32 v[14:15], v[170:171], v[142:143], v[14:15] op_sel_hi:[0,1,1]
	ds_read_b128 v[168:171], v176 offset:4032
	global_store_dwordx4 v177, v[140:143], s[16:17] nt
	s_add_u32 s16, s16, 0x800
	s_addc_u32 s17, s17, 0
	s_waitcnt vmcnt(31)
	s_waitcnt lgkmcnt(1)
	v_pk_mul_f32 v[172:173], v[164:165], v[148:149] op_sel:[1,0] op_sel_hi:[1,1]
	v_pk_mul_f32 v[174:175], v[164:165], v[150:151] op_sel:[1,0] op_sel_hi:[1,1]
	v_pk_fma_f32 v[144:145], v[164:165], v[144:145], v[172:173] op_sel_hi:[0,1,1]
	v_pk_fma_f32 v[146:147], v[164:165], v[146:147], v[174:175] op_sel_hi:[0,1,1]
	v_pk_fma_f32 v[0:1], v[166:167], v[144:145], v[0:1] op_sel_hi:[0,1,1]
	v_pk_fma_f32 v[2:3], v[166:167], v[146:147], v[2:3] op_sel_hi:[0,1,1]
	ds_read_b128 v[164:167], v176 offset:6080
	s_waitcnt lgkmcnt(1)
	v_pk_mul_f32 v[172:173], v[168:169], v[152:153] op_sel:[1,0] op_sel_hi:[1,1]
	v_pk_mul_f32 v[174:175], v[168:169], v[154:155] op_sel:[1,0] op_sel_hi:[1,1]
	v_pk_fma_f32 v[144:145], v[168:169], v[144:145], v[172:173] op_sel_hi:[0,1,1]
	v_pk_fma_f32 v[146:147], v[168:169], v[146:147], v[174:175] op_sel_hi:[0,1,1]
	v_pk_fma_f32 v[4:5], v[170:171], v[144:145], v[4:5] op_sel_hi:[0,1,1]
	v_pk_fma_f32 v[6:7], v[170:171], v[146:147], v[6:7] op_sel_hi:[0,1,1]
	ds_read_b128 v[168:171], v176 offset:8128
	s_waitcnt lgkmcnt(1)
	v_pk_mul_f32 v[172:173], v[164:165], v[156:157] op_sel:[1,0] op_sel_hi:[1,1]
	v_pk_mul_f32 v[174:175], v[164:165], v[158:159] op_sel:[1,0] op_sel_hi:[1,1]
	v_pk_fma_f32 v[144:145], v[164:165], v[144:145], v[172:173] op_sel_hi:[0,1,1]
	v_pk_fma_f32 v[146:147], v[164:165], v[146:147], v[174:175] op_sel_hi:[0,1,1]
	v_pk_fma_f32 v[8:9], v[166:167], v[144:145], v[8:9] op_sel_hi:[0,1,1]
	v_pk_fma_f32 v[10:11], v[166:167], v[146:147], v[10:11] op_sel_hi:[0,1,1]
	s_waitcnt lgkmcnt(0)
	v_pk_mul_f32 v[172:173], v[168:169], v[160:161] op_sel:[1,0] op_sel_hi:[1,1]
	v_pk_mul_f32 v[174:175], v[168:169], v[162:163] op_sel:[1,0] op_sel_hi:[1,1]
	v_pk_fma_f32 v[144:145], v[168:169], v[144:145], v[172:173] op_sel_hi:[0,1,1]
	v_pk_fma_f32 v[146:147], v[168:169], v[146:147], v[174:175] op_sel_hi:[0,1,1]
	v_pk_fma_f32 v[12:13], v[170:171], v[144:145], v[12:13] op_sel_hi:[0,1,1]
	v_pk_fma_f32 v[14:15], v[170:171], v[146:147], v[14:15] op_sel_hi:[0,1,1]
	global_store_dwordx4 v177, v[144:147], s[16:17] nt
	v_lshrrev_b32_e32 v18, 4, v191
	v_and_b32_e32 v19, 15, v191
	v_lshlrev_b32_e32 v16, 8, v18
	v_lshl_add_u32 v16, v19, 4, v16
	v_add_u32_e32 v16, s30, v16
	ds_write_b128 v16, v[0:3] offset:8192
	ds_write_b128 v16, v[4:7] offset:9216
	ds_write_b128 v16, v[8:11] offset:10240
	ds_write_b128 v16, v[12:15] offset:11264
	v_lshlrev_b32_e32 v16, 10, v18
	v_lshl_add_u32 v16, v19, 4, v16
	v_add_u32_e32 v16, s30, v16
	s_waitcnt lgkmcnt(0)
	ds_read_b128 v[20:23], v16 offset:8192
	ds_read_b128 v[24:27], v16 offset:8448
	ds_read_b128 v[28:31], v16 offset:8704
	ds_read_b128 v[32:35], v16 offset:8960
	s_lshl_b32 s0, s47, 9
	s_add_i32 s0, s0, s46
	s_add_i32 s0, s0, s14
	v_lshlrev_b32_e32 v42, 9, v18
	v_lshl_add_u32 v42, v19, 2, v42
	v_add_u32_e32 v42, s0, v42
	v_lshlrev_b32_e32 v42, 1, v42
	v_add_u32_e32 v43, 0x880000, v42
	s_waitcnt lgkmcnt(0)
	v_pk_add_f32 v[20:21], v[20:21], v[24:25]
	v_pk_add_f32 v[22:23], v[22:23], v[26:27]
	v_pk_add_f32 v[28:29], v[28:29], v[32:33]
	v_pk_add_f32 v[30:31], v[30:31], v[34:35]
	v_pk_add_f32 v[20:21], v[20:21], v[28:29]
	v_pk_add_f32 v[22:23], v[22:23], v[30:31]
	s_nop 1
	v_cvt_pk_bf16_f32 v36, v20, v21
	v_cvt_pk_bf16_f32 v37, v22, v23
	s_nop 0
	v_lshlrev_b32_e32 v38, 16, v36
	v_and_b32_e32 v39, 0xffff0000, v36
	v_lshlrev_b32_e32 v40, 16, v37
	v_and_b32_e32 v41, 0xffff0000, v37
	v_sub_f32_e32 v20, v20, v38
	v_sub_f32_e32 v21, v21, v39
	v_sub_f32_e32 v22, v22, v40
	v_sub_f32_e32 v23, v23, v41
	global_store_dwordx2 v42, v[36:37], s[8:9]
	v_cvt_pk_bf16_f32 v38, v20, v21
	v_cvt_pk_bf16_f32 v39, v22, v23
	s_nop 0
	global_store_dwordx2 v43, v[38:39], s[8:9]
	s_waitcnt lgkmcnt(0)
	s_branch .LBB0_629
